# v42 + GEMM K-loop counter/pointer SALU in front of the loop-back barrier
# baseline (speedup 1.0000x reference)
; #define PG8_STAGE(bufoff, gbase, voff) do { _Pragma("unroll") for (int _i = 0; _i < 2; ++_i) \
;         __builtin_amdgcn_global_load_lds((const unsigned*)((const char*)(gbase) + (voff)[_i]), (PG8_LAS unsigned*)(lds + (bufoff) + ldsw + _i * 8192), 16, 0, 0); } while (0)
; #define PG8_LDA(dst, b, h) do { _Pragma("unroll") for (int m = 0; m < 4; ++m) _Pragma("unroll") for (int k = 0; k < 2; ++k) dst[m][k] = *(const PG8_LAS bf16x8*)(lds + PG8_SA(b, h) + aoff + m * 2048 + k * 1024); } while (0)
; #define PG8_LDB(dst, b, h) do { _Pragma("unroll") for (int n = 0; n < 2; ++n) _Pragma("unroll") for (int k = 0; k < 2; ++k) dst[n][k] = *(const PG8_LAS bf16x8*)(lds + PG8_SB(b, h) + boff + n * 2048 + k * 1024); } while (0)
; #define PG8_WAIT_V(n) asm volatile("s_waitcnt vmcnt(" #n ")" ::: "memory")
; #define PG8_WAIT_L(n) asm volatile("s_waitcnt lgkmcnt(" #n ")" ::: "memory")
; #define PG8_BAR __builtin_amdgcn_s_barrier()
; #define PG8_SCHED __builtin_amdgcn_sched_barrier(0)
; template <class Epi, class Sched, bool ALIGN_EPI = false, bool SP2 = false>
; __device__ __forceinline__ void gemm_phase(PG8_LAS unsigned char* lds, const Gemm g, const Sched& S, const Epi& E) {
;     ...
;         const bool has_next = S.next(ui + 1, nxt);
;         const char* nA = has_next ? (const char*)g.A + (size_t)nxt.pm * tstep : cA; const char* nB = has_next ? (const char*)g.Bt + (size_t)nxt.pn * tstep : cB;
;         for (int t = 0; t < nt; t += 2) {
;             const bool last = (t == nt - 2);
;             const char* a1 = cA + (size_t)(t + 1) * kstep;
;             const char* a2 = last ? nA : cA + (size_t)(t + 2) * kstep; const char* b2 = last ? nB : cB + (size_t)(t + 2) * kstep;
;             const char* a3 = a2 + kstep; const char* b3 = b2 + kstep;
;             if (last && has_next) S.a_ready(nxt);
;             if constexpr (SP2) {
;             PG8_LDB(B0, 0, 0); PG8_LDB(B1, 0, 1); PG8_SCHED; PG8_LDA(At, 0, 0); PG8_STAGE(PG8_SA(1, 1), a1 + hstep, voffA);
;             PG8_WAIT_V(8); PG8_WAIT_L(0); PG8_BAR; PG8_MMA(0, 0, At, B0); PG8_MMA(0, 1, At, B1); PG8_BAR; PG8_SCHED;
;             PG8_LDA(At, 0, 1); PG8_STAGE(PG8_SB(0, 0), b2, voffB); PG8_STAGE(PG8_SB(0, 1), b2 + hstep, voffB); PG8_STAGE(PG8_SA(0, 0), a2, voffA);
;             PG8_WAIT_V(8); PG8_WAIT_L(0); PG8_BAR; PG8_MMA(1, 0, At, B0); PG8_MMA(1, 1, At, B1); PG8_BAR; PG8_SCHED;
.LBB0_124:
	ds_read_b128 v[150:153], v161
	ds_read_b128 v[154:157], v223
	ds_read_b128 v[166:169], v161 offset:2048
	ds_read_b128 v[170:173], v223 offset:2048
	ds_read_b128 v[174:177], v162
	ds_read_b128 v[178:181], v224
	ds_read_b128 v[182:185], v162 offset:2048
	ds_read_b128 v[186:189], v224 offset:2048
	s_add_u32 s4, s36, 0xfff80080
	s_addc_u32 s5, s37, -1
	s_cmp_eq_u32 s69, 28
	s_cselect_b32 s41, s9, s5
	s_cselect_b32 s40, s27, s4
	s_cselect_b32 s39, s25, s68
	s_cselect_b32 s38, s35, s67
	s_add_i32 m0, s58, 0x80
	s_nop 0
	global_load_lds_dwordx4 v130, s[4:5] offset:-128
	s_add_i32 m0, s59, 0x80
	s_nop 0
	global_load_lds_dwordx4 v134, s[4:5] offset:-128
	s_add_i32 m0, s49, 0xc000
	ds_read_b128 v[190:193], v163
	ds_read_b128 v[194:197], v222
	ds_read_b128 v[198:201], v163 offset:2048
	ds_read_b128 v[202:205], v222 offset:2048
	ds_read_b128 v[206:209], v163 offset:4096
	ds_read_b128 v[210:213], v222 offset:4096
	ds_read_b128 v[214:217], v163 offset:6144
	ds_read_b128 v[218:221], v222 offset:6144
	global_load_lds_dwordx4 v140, s[36:37]
	s_add_i32 m0, s49, 0xe000
	s_nop 0
	global_load_lds_dwordx4 v142, s[36:37]
	s_waitcnt vmcnt(8)
	s_waitcnt lgkmcnt(0)
	s_barrier
	s_setprio 1
	s_waitcnt lgkmcnt(0)
	v_mfma_f32_16x16x32_bf16 v[126:129], v[150:153], v[190:193], v[126:129]
	v_mfma_f32_16x16x32_bf16 v[122:125], v[166:169], v[190:193], v[122:125]
	v_mfma_f32_16x16x32_bf16 v[110:113], v[150:153], v[198:201], v[110:113]
	v_mfma_f32_16x16x32_bf16 v[106:109], v[166:169], v[198:201], v[106:109]
	v_mfma_f32_16x16x32_bf16 v[94:97], v[150:153], v[206:209], v[94:97]
	v_mfma_f32_16x16x32_bf16 v[90:93], v[166:169], v[206:209], v[90:93]
	v_mfma_f32_16x16x32_bf16 v[78:81], v[150:153], v[214:217], v[78:81]
	v_mfma_f32_16x16x32_bf16 v[74:77], v[166:169], v[214:217], v[74:77]
	v_mfma_f32_16x16x32_bf16 v[126:129], v[154:157], v[194:197], v[126:129]
	v_mfma_f32_16x16x32_bf16 v[122:125], v[170:173], v[194:197], v[122:125]
	v_mfma_f32_16x16x32_bf16 v[110:113], v[154:157], v[202:205], v[110:113]
	v_mfma_f32_16x16x32_bf16 v[106:109], v[170:173], v[202:205], v[106:109]
	v_mfma_f32_16x16x32_bf16 v[94:97], v[154:157], v[210:213], v[94:97]
	v_mfma_f32_16x16x32_bf16 v[90:93], v[170:173], v[210:213], v[90:93]
	v_mfma_f32_16x16x32_bf16 v[78:81], v[154:157], v[218:221], v[78:81]
	v_mfma_f32_16x16x32_bf16 v[74:77], v[170:173], v[218:221], v[74:77]
	s_setprio 0
	s_setprio 1
	v_mfma_f32_16x16x32_bf16 v[118:121], v[174:177], v[190:193], v[118:121]
	v_mfma_f32_16x16x32_bf16 v[114:117], v[182:185], v[190:193], v[114:117]
	v_mfma_f32_16x16x32_bf16 v[102:105], v[174:177], v[198:201], v[102:105]
	v_mfma_f32_16x16x32_bf16 v[98:101], v[182:185], v[198:201], v[98:101]
	v_mfma_f32_16x16x32_bf16 v[86:89], v[174:177], v[206:209], v[86:89]
	v_mfma_f32_16x16x32_bf16 v[82:85], v[182:185], v[206:209], v[82:85]
	v_mfma_f32_16x16x32_bf16 v[70:73], v[174:177], v[214:217], v[70:73]
	v_mfma_f32_16x16x32_bf16 v[66:69], v[182:185], v[214:217], v[66:69]
	v_mfma_f32_16x16x32_bf16 v[118:121], v[178:181], v[194:197], v[118:121]
	v_mfma_f32_16x16x32_bf16 v[114:117], v[186:189], v[194:197], v[114:117]
	v_mfma_f32_16x16x32_bf16 v[102:105], v[178:181], v[202:205], v[102:105]
	v_mfma_f32_16x16x32_bf16 v[98:101], v[186:189], v[202:205], v[98:101]
	v_mfma_f32_16x16x32_bf16 v[86:89], v[178:181], v[210:213], v[86:89]
	v_mfma_f32_16x16x32_bf16 v[82:85], v[186:189], v[210:213], v[82:85]
	v_mfma_f32_16x16x32_bf16 v[70:73], v[178:181], v[218:221], v[70:73]
	v_mfma_f32_16x16x32_bf16 v[66:69], v[186:189], v[218:221], v[66:69]
	s_setprio 0
	s_barrier
	s_add_i32 s4, s64, s48
	s_mov_b32 m0, s4
	ds_read_b128 v[190:193], v163 offset:16384
	ds_read_b128 v[194:197], v222 offset:16384
	ds_read_b128 v[198:201], v163 offset:18432
	ds_read_b128 v[202:205], v222 offset:18432
	ds_read_b128 v[206:209], v163 offset:20480
	ds_read_b128 v[210:213], v222 offset:20480
	ds_read_b128 v[214:217], v163 offset:22528
	ds_read_b128 v[218:221], v222 offset:22528
	global_load_lds_dwordx4 v132, s[38:39]
	s_add_i32 m0, s4, 0x2000
	s_add_u32 s70, s38, 0x80000
	s_addc_u32 s71, s39, 0
	s_add_i32 s4, s65, s48
	global_load_lds_dwordx4 v136, s[38:39]
	s_mov_b32 m0, s4
	s_nop 0
	global_load_lds_dwordx4 v132, s[70:71]
	s_add_i32 m0, s4, 0x2000
	s_nop 0
	global_load_lds_dwordx4 v136, s[70:71]
	s_waitcnt vmcnt(6)
	s_waitcnt lgkmcnt(0)
	s_barrier
	s_setprio 1
	s_waitcnt lgkmcnt(0)
	v_mfma_f32_16x16x32_bf16 v[62:65], v[150:153], v[190:193], v[62:65]
	v_mfma_f32_16x16x32_bf16 v[58:61], v[166:169], v[190:193], v[58:61]
	v_mfma_f32_16x16x32_bf16 v[46:49], v[150:153], v[198:201], v[46:49]
	v_mfma_f32_16x16x32_bf16 v[42:45], v[166:169], v[198:201], v[42:45]
	v_mfma_f32_16x16x32_bf16 v[30:33], v[150:153], v[206:209], v[30:33]
	v_mfma_f32_16x16x32_bf16 v[26:29], v[166:169], v[206:209], v[26:29]
	v_mfma_f32_16x16x32_bf16 v[14:17], v[150:153], v[214:217], v[14:17]
	v_mfma_f32_16x16x32_bf16 v[10:13], v[166:169], v[214:217], v[10:13]
	v_mfma_f32_16x16x32_bf16 v[62:65], v[154:157], v[194:197], v[62:65]
	v_mfma_f32_16x16x32_bf16 v[58:61], v[170:173], v[194:197], v[58:61]
	v_mfma_f32_16x16x32_bf16 v[46:49], v[154:157], v[202:205], v[46:49]
	v_mfma_f32_16x16x32_bf16 v[42:45], v[170:173], v[202:205], v[42:45]
	v_mfma_f32_16x16x32_bf16 v[30:33], v[154:157], v[210:213], v[30:33]
	v_mfma_f32_16x16x32_bf16 v[26:29], v[170:173], v[210:213], v[26:29]
	v_mfma_f32_16x16x32_bf16 v[14:17], v[154:157], v[218:221], v[14:17]
	v_mfma_f32_16x16x32_bf16 v[10:13], v[170:173], v[218:221], v[10:13]
	s_setprio 0
	s_setprio 1
	v_mfma_f32_16x16x32_bf16 v[54:57], v[174:177], v[190:193], v[54:57]
	v_mfma_f32_16x16x32_bf16 v[50:53], v[182:185], v[190:193], v[50:53]
	v_mfma_f32_16x16x32_bf16 v[38:41], v[174:177], v[198:201], v[38:41]
	v_mfma_f32_16x16x32_bf16 v[34:37], v[182:185], v[198:201], v[34:37]
	v_mfma_f32_16x16x32_bf16 v[22:25], v[174:177], v[206:209], v[22:25]
	v_mfma_f32_16x16x32_bf16 v[18:21], v[182:185], v[206:209], v[18:21]
	v_mfma_f32_16x16x32_bf16 v[6:9], v[174:177], v[214:217], v[6:9]
	v_mfma_f32_16x16x32_bf16 v[2:5], v[182:185], v[214:217], v[2:5]
	v_mfma_f32_16x16x32_bf16 v[54:57], v[178:181], v[194:197], v[54:57]
	v_mfma_f32_16x16x32_bf16 v[50:53], v[186:189], v[194:197], v[50:53]
	v_mfma_f32_16x16x32_bf16 v[38:41], v[178:181], v[202:205], v[38:41]
	v_mfma_f32_16x16x32_bf16 v[34:37], v[186:189], v[202:205], v[34:37]
	v_mfma_f32_16x16x32_bf16 v[22:25], v[178:181], v[210:213], v[22:25]
	v_mfma_f32_16x16x32_bf16 v[18:21], v[186:189], v[210:213], v[18:21]
	v_mfma_f32_16x16x32_bf16 v[6:9], v[178:181], v[218:221], v[6:9]
	v_mfma_f32_16x16x32_bf16 v[2:5], v[186:189], v[218:221], v[2:5]
	s_setprio 0
	s_barrier
; #define PG8_STAGE(bufoff, gbase, voff) do { _Pragma("unroll") for (int _i = 0; _i < 2; ++_i) \
;         __builtin_amdgcn_global_load_lds((const unsigned*)((const char*)(gbase) + (voff)[_i]), (PG8_LAS unsigned*)(lds + (bufoff) + ldsw + _i * 8192), 16, 0, 0); } while (0)
; #define PG8_LDA(dst, b, h) do { _Pragma("unroll") for (int m = 0; m < 4; ++m) _Pragma("unroll") for (int k = 0; k < 2; ++k) dst[m][k] = *(const PG8_LAS bf16x8*)(lds + PG8_SA(b, h) + aoff + m * 2048 + k * 1024); } while (0)
; #define PG8_LDB(dst, b, h) do { _Pragma("unroll") for (int n = 0; n < 2; ++n) _Pragma("unroll") for (int k = 0; k < 2; ++k) dst[n][k] = *(const PG8_LAS bf16x8*)(lds + PG8_SB(b, h) + boff + n * 2048 + k * 1024); } while (0)
; #define PG8_MMA(ai, bj, At, Bt) do { __builtin_amdgcn_s_setprio(1); _Pragma("unroll") for (int m = 0; m < 4; ++m) _Pragma("unroll") for (int n = 0; n < 2; ++n) _Pragma("unroll") for (int k = 0; k < 2; ++k) \
;         acc[ai][bj][m][n] = __builtin_amdgcn_mfma_f32_16x16x32_bf16(Bt[n][k], At[m][k], acc[ai][bj][m][n], 0, 0, 0); __builtin_amdgcn_s_setprio(0); } while (0)
; #define PG8_WAIT_V(n) asm volatile("s_waitcnt vmcnt(" #n ")" ::: "memory")
; #define PG8_WAIT_L(n) asm volatile("s_waitcnt lgkmcnt(" #n ")" ::: "memory")
; #define PG8_BAR __builtin_amdgcn_s_barrier()
; template <class Epi, class Sched, bool ALIGN_EPI = false, bool SP2 = false>
; __device__ __forceinline__ void gemm_phase(PG8_LAS unsigned char* lds, const Gemm g, const Sched& S, const Epi& E) {
;     ...
;         for (int t = 0; t < nt; t += 2) {
;             const bool last = (t == nt - 2);
;             const char* a1 = cA + (size_t)(t + 1) * kstep;
;             const char* a2 = last ? nA : cA + (size_t)(t + 2) * kstep; const char* b2 = last ? nB : cB + (size_t)(t + 2) * kstep;
;             const char* a3 = a2 + kstep; const char* b3 = b2 + kstep;
;     ...
;             PG8_LDB(B0, 1, 0); PG8_LDB(B1, 1, 1); PG8_SCHED; PG8_LDA(At, 1, 0); PG8_STAGE(PG8_SA(0, 1), a2 + hstep, voffA);
;             PG8_WAIT_V(8); PG8_WAIT_L(0); PG8_BAR; PG8_MMA(0, 0, At, B0); PG8_MMA(0, 1, At, B1); PG8_BAR; PG8_SCHED;
;             PG8_LDA(At, 1, 1); PG8_STAGE(PG8_SB(1, 0), b3, voffB); PG8_STAGE(PG8_SB(1, 1), b3 + hstep, voffB); PG8_STAGE(PG8_SA(1, 0), a3, voffA);
;             PG8_WAIT_V(8); PG8_WAIT_L(0); PG8_BAR; PG8_MMA(1, 0, At, B0); PG8_MMA(1, 1, At, B1); PG8_BAR; PG8_SCHED;
	s_add_i32 s4, 0, 0x18000
	s_add_i32 s5, 0, 0x1c000
	ds_read_b128 v[150:153], v225
	ds_read_b128 v[154:157], v226
	ds_read_b128 v[166:169], v225 offset:2048
	ds_read_b128 v[170:173], v226 offset:2048
	ds_read_b128 v[174:177], v227
	ds_read_b128 v[178:181], v228
	ds_read_b128 v[182:185], v227 offset:2048
	ds_read_b128 v[186:189], v228 offset:2048
	s_add_u32 s70, s40, 0x80000
	s_addc_u32 s71, s41, 0
	s_mov_b32 m0, s49
	s_nop 0
	global_load_lds_dwordx4 v130, s[40:41]
	s_mov_b32 m0, s50
	s_nop 0
	global_load_lds_dwordx4 v134, s[40:41]
	s_mov_b32 m0, s51
	ds_read_b128 v[190:193], v163 offset:32768
	ds_read_b128 v[194:197], v222 offset:32768
	ds_read_b128 v[198:201], v163 offset:34816
	ds_read_b128 v[202:205], v222 offset:34816
	ds_read_b128 v[206:209], v163 offset:36864
	ds_read_b128 v[210:213], v222 offset:36864
	ds_read_b128 v[214:217], v163 offset:38912
	ds_read_b128 v[218:221], v222 offset:38912
	global_load_lds_dwordx4 v130, s[70:71]
	s_mov_b32 m0, s52
	s_nop 0
	global_load_lds_dwordx4 v134, s[70:71]
	s_waitcnt vmcnt(8)
	s_waitcnt lgkmcnt(0)
	s_barrier
	s_setprio 1
	s_waitcnt lgkmcnt(0)
	v_mfma_f32_16x16x32_bf16 v[126:129], v[150:153], v[190:193], v[126:129]
	v_mfma_f32_16x16x32_bf16 v[122:125], v[166:169], v[190:193], v[122:125]
	v_mfma_f32_16x16x32_bf16 v[110:113], v[150:153], v[198:201], v[110:113]
	v_mfma_f32_16x16x32_bf16 v[106:109], v[166:169], v[198:201], v[106:109]
	v_mfma_f32_16x16x32_bf16 v[94:97], v[150:153], v[206:209], v[94:97]
	v_mfma_f32_16x16x32_bf16 v[90:93], v[166:169], v[206:209], v[90:93]
	v_mfma_f32_16x16x32_bf16 v[78:81], v[150:153], v[214:217], v[78:81]
	v_mfma_f32_16x16x32_bf16 v[74:77], v[166:169], v[214:217], v[74:77]
	v_mfma_f32_16x16x32_bf16 v[126:129], v[154:157], v[194:197], v[126:129]
	v_mfma_f32_16x16x32_bf16 v[122:125], v[170:173], v[194:197], v[122:125]
	v_mfma_f32_16x16x32_bf16 v[110:113], v[154:157], v[202:205], v[110:113]
	v_mfma_f32_16x16x32_bf16 v[106:109], v[170:173], v[202:205], v[106:109]
	v_mfma_f32_16x16x32_bf16 v[94:97], v[154:157], v[210:213], v[94:97]
	v_mfma_f32_16x16x32_bf16 v[90:93], v[170:173], v[210:213], v[90:93]
	v_mfma_f32_16x16x32_bf16 v[78:81], v[154:157], v[218:221], v[78:81]
	v_mfma_f32_16x16x32_bf16 v[74:77], v[170:173], v[218:221], v[74:77]
	s_setprio 0
	s_setprio 1
	v_mfma_f32_16x16x32_bf16 v[118:121], v[174:177], v[190:193], v[118:121]
	v_mfma_f32_16x16x32_bf16 v[114:117], v[182:185], v[190:193], v[114:117]
	v_mfma_f32_16x16x32_bf16 v[102:105], v[174:177], v[198:201], v[102:105]
	v_mfma_f32_16x16x32_bf16 v[98:101], v[182:185], v[198:201], v[98:101]
	v_mfma_f32_16x16x32_bf16 v[86:89], v[174:177], v[206:209], v[86:89]
	v_mfma_f32_16x16x32_bf16 v[82:85], v[182:185], v[206:209], v[82:85]
	v_mfma_f32_16x16x32_bf16 v[70:73], v[174:177], v[214:217], v[70:73]
	v_mfma_f32_16x16x32_bf16 v[66:69], v[182:185], v[214:217], v[66:69]
	v_mfma_f32_16x16x32_bf16 v[118:121], v[178:181], v[194:197], v[118:121]
	v_mfma_f32_16x16x32_bf16 v[114:117], v[186:189], v[194:197], v[114:117]
	v_mfma_f32_16x16x32_bf16 v[102:105], v[178:181], v[202:205], v[102:105]
	v_mfma_f32_16x16x32_bf16 v[98:101], v[186:189], v[202:205], v[98:101]
	v_mfma_f32_16x16x32_bf16 v[86:89], v[178:181], v[210:213], v[86:89]
	v_mfma_f32_16x16x32_bf16 v[82:85], v[186:189], v[210:213], v[82:85]
	v_mfma_f32_16x16x32_bf16 v[70:73], v[178:181], v[218:221], v[70:73]
	v_mfma_f32_16x16x32_bf16 v[66:69], v[186:189], v[218:221], v[66:69]
	s_setprio 0
	s_barrier
	s_add_i32 s4, s4, s48
	s_add_i32 m0, s4, 0xffffff80
	ds_read_b128 v[190:193], v163 offset:49152
	ds_read_b128 v[194:197], v222 offset:49152
	ds_read_b128 v[198:201], v163 offset:51200
	ds_read_b128 v[202:205], v222 offset:51200
	ds_read_b128 v[206:209], v163 offset:53248
	ds_read_b128 v[210:213], v222 offset:53248
	ds_read_b128 v[214:217], v163 offset:55296
	ds_read_b128 v[218:221], v222 offset:55296
	global_load_lds_dwordx4 v132, s[38:39] offset:128
	s_add_i32 m0, s4, 0x1f80
	s_nop 0
	global_load_lds_dwordx4 v136, s[38:39] offset:128
	s_add_u32 s38, s38, 0x80080
	s_addc_u32 s39, s39, 0
	s_add_i32 s4, s5, s48
	s_mov_b32 m0, s4
	s_nop 0
	global_load_lds_dwordx4 v132, s[38:39]
	s_add_i32 m0, s4, 0x2000
	s_nop 0
	global_load_lds_dwordx4 v136, s[38:39]
	s_waitcnt vmcnt(6)
	s_waitcnt lgkmcnt(0)
	s_barrier
	s_setprio 1
	s_waitcnt lgkmcnt(0)
	v_mfma_f32_16x16x32_bf16 v[62:65], v[150:153], v[190:193], v[62:65]
	v_mfma_f32_16x16x32_bf16 v[58:61], v[166:169], v[190:193], v[58:61]
	v_mfma_f32_16x16x32_bf16 v[46:49], v[150:153], v[198:201], v[46:49]
	v_mfma_f32_16x16x32_bf16 v[42:45], v[166:169], v[198:201], v[42:45]
	v_mfma_f32_16x16x32_bf16 v[30:33], v[150:153], v[206:209], v[30:33]
	v_mfma_f32_16x16x32_bf16 v[26:29], v[166:169], v[206:209], v[26:29]
	v_mfma_f32_16x16x32_bf16 v[14:17], v[150:153], v[214:217], v[14:17]
	v_mfma_f32_16x16x32_bf16 v[10:13], v[166:169], v[214:217], v[10:13]
	v_mfma_f32_16x16x32_bf16 v[62:65], v[154:157], v[194:197], v[62:65]
	v_mfma_f32_16x16x32_bf16 v[58:61], v[170:173], v[194:197], v[58:61]
	v_mfma_f32_16x16x32_bf16 v[46:49], v[154:157], v[202:205], v[46:49]
	v_mfma_f32_16x16x32_bf16 v[42:45], v[170:173], v[202:205], v[42:45]
	v_mfma_f32_16x16x32_bf16 v[30:33], v[154:157], v[210:213], v[30:33]
	v_mfma_f32_16x16x32_bf16 v[26:29], v[170:173], v[210:213], v[26:29]
	v_mfma_f32_16x16x32_bf16 v[14:17], v[154:157], v[218:221], v[14:17]
	v_mfma_f32_16x16x32_bf16 v[10:13], v[170:173], v[218:221], v[10:13]
	s_setprio 0
	s_setprio 1
	v_mfma_f32_16x16x32_bf16 v[54:57], v[174:177], v[190:193], v[54:57]
	v_mfma_f32_16x16x32_bf16 v[50:53], v[182:185], v[190:193], v[50:53]
	v_mfma_f32_16x16x32_bf16 v[38:41], v[174:177], v[198:201], v[38:41]
	v_mfma_f32_16x16x32_bf16 v[34:37], v[182:185], v[198:201], v[34:37]
	v_mfma_f32_16x16x32_bf16 v[22:25], v[174:177], v[206:209], v[22:25]
	v_mfma_f32_16x16x32_bf16 v[18:21], v[182:185], v[206:209], v[18:21]
	v_mfma_f32_16x16x32_bf16 v[6:9], v[174:177], v[214:217], v[6:9]
	v_mfma_f32_16x16x32_bf16 v[2:5], v[182:185], v[214:217], v[2:5]
	v_mfma_f32_16x16x32_bf16 v[54:57], v[178:181], v[194:197], v[54:57]
	v_mfma_f32_16x16x32_bf16 v[50:53], v[186:189], v[194:197], v[50:53]
	v_mfma_f32_16x16x32_bf16 v[38:41], v[178:181], v[202:205], v[38:41]
	v_mfma_f32_16x16x32_bf16 v[34:37], v[186:189], v[202:205], v[34:37]
	v_mfma_f32_16x16x32_bf16 v[22:25], v[178:181], v[210:213], v[22:25]
	v_mfma_f32_16x16x32_bf16 v[18:21], v[186:189], v[210:213], v[18:21]
	v_mfma_f32_16x16x32_bf16 v[6:9], v[178:181], v[218:221], v[6:9]
	v_mfma_f32_16x16x32_bf16 v[2:5], v[186:189], v[218:221], v[2:5]
	s_setprio 0
	s_add_i32 s69, s69, 2
	s_add_u32 s36, s36, 0x100
	s_addc_u32 s37, s37, 0
	s_add_u32 s67, s67, 0x100
	s_addc_u32 s68, s68, 0
	s_cmp_gt_u32 s69, 29
	s_barrier
	s_cbranch_scc0 .LBB0_124
	s_and_b64 vcc, exec, s[22:23]
	s_cbranch_vccz .LBB0_127
	s_barrier

; #define PG8_STAGE(bufoff, gbase, voff) do { _Pragma("unroll") for (int _i = 0; _i < 2; ++_i) \
;         __builtin_amdgcn_global_load_lds((const unsigned*)((const char*)(gbase) + (voff)[_i]), (PG8_LAS unsigned*)(lds + (bufoff) + ldsw + _i * 8192), 16, 0, 0); } while (0)
; #define PG8_LDA(dst, b, h) do { _Pragma("unroll") for (int m = 0; m < 4; ++m) _Pragma("unroll") for (int k = 0; k < 2; ++k) dst[m][k] = *(const PG8_LAS bf16x8*)(lds + PG8_SA(b, h) + aoff + m * 2048 + k * 1024); } while (0)
; #define PG8_LDB(dst, b, h) do { _Pragma("unroll") for (int n = 0; n < 2; ++n) _Pragma("unroll") for (int k = 0; k < 2; ++k) dst[n][k] = *(const PG8_LAS bf16x8*)(lds + PG8_SB(b, h) + boff + n * 2048 + k * 1024); } while (0)
; #define PG8_WAIT_V(n) asm volatile("s_waitcnt vmcnt(" #n ")" ::: "memory")
; #define PG8_WAIT_L(n) asm volatile("s_waitcnt lgkmcnt(" #n ")" ::: "memory")
; #define PG8_BAR __builtin_amdgcn_s_barrier()
; #define PG8_SCHED __builtin_amdgcn_sched_barrier(0)
; template <class Epi, class Sched, bool ALIGN_EPI = false, bool SP2 = false>
; __device__ __forceinline__ void gemm_phase(PG8_LAS unsigned char* lds, const Gemm g, const Sched& S, const Epi& E) {
;     ...
;         const bool has_next = S.next(ui + 1, nxt);
;         const char* nA = has_next ? (const char*)g.A + (size_t)nxt.pm * tstep : cA; const char* nB = has_next ? (const char*)g.Bt + (size_t)nxt.pn * tstep : cB;
;         for (int t = 0; t < nt; t += 2) {
;             const bool last = (t == nt - 2);
;             const char* a1 = cA + (size_t)(t + 1) * kstep;
;             const char* a2 = last ? nA : cA + (size_t)(t + 2) * kstep; const char* b2 = last ? nB : cB + (size_t)(t + 2) * kstep;
;             const char* a3 = a2 + kstep; const char* b3 = b2 + kstep;
;             if (last && has_next) S.a_ready(nxt);
;             if constexpr (SP2) {
;             PG8_LDB(B0, 0, 0); PG8_LDB(B1, 0, 1); PG8_SCHED; PG8_LDA(At, 0, 0); PG8_STAGE(PG8_SA(1, 1), a1 + hstep, voffA);
;             PG8_WAIT_V(8); PG8_WAIT_L(0); PG8_BAR; PG8_MMA(0, 0, At, B0); PG8_MMA(0, 1, At, B1); PG8_BAR; PG8_SCHED;
;             PG8_LDA(At, 0, 1); PG8_STAGE(PG8_SB(0, 0), b2, voffB); PG8_STAGE(PG8_SB(0, 1), b2 + hstep, voffB); PG8_STAGE(PG8_SA(0, 0), a2, voffA);
;             PG8_WAIT_V(8); PG8_WAIT_L(0); PG8_BAR; PG8_MMA(1, 0, At, B0); PG8_MMA(1, 1, At, B1); PG8_BAR; PG8_SCHED;
.LBB0_763:
	ds_read_b128 v[154:157], v150
	ds_read_b128 v[158:161], v147
	ds_read_b128 v[162:165], v150 offset:2048
	ds_read_b128 v[166:169], v147 offset:2048
	ds_read_b128 v[170:173], v151
	ds_read_b128 v[174:177], v218
	ds_read_b128 v[178:181], v151 offset:2048
	ds_read_b128 v[182:185], v218 offset:2048
	s_add_u32 s4, s40, 0xfff80080
	s_addc_u32 s5, s41, -1
	s_cmp_eq_u32 s78, 28
	s_cselect_b32 s51, s31, s5
	s_cselect_b32 s50, s74, s4
	s_cselect_b32 s49, s29, s77
	s_cselect_b32 s48, s75, s76
	s_add_i32 m0, s63, 0x80
	s_nop 0
	global_load_lds_dwordx4 v130, s[4:5] offset:-128
	s_add_i32 m0, s64, 0x80
	s_nop 0
	global_load_lds_dwordx4 v134, s[4:5] offset:-128
	s_add_i32 m0, s39, 0xc000
	ds_read_b128 v[186:189], v152
	ds_read_b128 v[190:193], v146
	ds_read_b128 v[194:197], v152 offset:2048
	ds_read_b128 v[198:201], v146 offset:2048
	ds_read_b128 v[202:205], v152 offset:4096
	ds_read_b128 v[206:209], v146 offset:4096
	ds_read_b128 v[210:213], v152 offset:6144
	ds_read_b128 v[214:217], v146 offset:6144
	global_load_lds_dwordx4 v138, s[40:41]
	s_add_i32 m0, s39, 0xe000
	s_nop 0
	global_load_lds_dwordx4 v140, s[40:41]
	s_waitcnt vmcnt(8)
	s_waitcnt lgkmcnt(0)
	s_barrier
	s_setprio 1
	s_waitcnt lgkmcnt(0)
	v_mfma_f32_16x16x32_bf16 v[126:129], v[154:157], v[186:189], v[126:129]
	v_mfma_f32_16x16x32_bf16 v[122:125], v[162:165], v[186:189], v[122:125]
	v_mfma_f32_16x16x32_bf16 v[114:117], v[154:157], v[194:197], v[114:117]
	v_mfma_f32_16x16x32_bf16 v[106:109], v[162:165], v[194:197], v[106:109]
	v_mfma_f32_16x16x32_bf16 v[98:101], v[154:157], v[202:205], v[98:101]
	v_mfma_f32_16x16x32_bf16 v[90:93], v[162:165], v[202:205], v[90:93]
	v_mfma_f32_16x16x32_bf16 v[82:85], v[154:157], v[210:213], v[82:85]
	v_mfma_f32_16x16x32_bf16 v[74:77], v[162:165], v[210:213], v[74:77]
	v_mfma_f32_16x16x32_bf16 v[126:129], v[158:161], v[190:193], v[126:129]
	v_mfma_f32_16x16x32_bf16 v[122:125], v[166:169], v[190:193], v[122:125]
	v_mfma_f32_16x16x32_bf16 v[114:117], v[158:161], v[198:201], v[114:117]
	v_mfma_f32_16x16x32_bf16 v[106:109], v[166:169], v[198:201], v[106:109]
	v_mfma_f32_16x16x32_bf16 v[98:101], v[158:161], v[206:209], v[98:101]
	v_mfma_f32_16x16x32_bf16 v[90:93], v[166:169], v[206:209], v[90:93]
	v_mfma_f32_16x16x32_bf16 v[82:85], v[158:161], v[214:217], v[82:85]
	v_mfma_f32_16x16x32_bf16 v[74:77], v[166:169], v[214:217], v[74:77]
	s_setprio 0
	s_setprio 1
	v_mfma_f32_16x16x32_bf16 v[118:121], v[170:173], v[186:189], v[118:121]
	v_mfma_f32_16x16x32_bf16 v[110:113], v[178:181], v[186:189], v[110:113]
	v_mfma_f32_16x16x32_bf16 v[102:105], v[170:173], v[194:197], v[102:105]
	v_mfma_f32_16x16x32_bf16 v[94:97], v[178:181], v[194:197], v[94:97]
	v_mfma_f32_16x16x32_bf16 v[86:89], v[170:173], v[202:205], v[86:89]
	v_mfma_f32_16x16x32_bf16 v[78:81], v[178:181], v[202:205], v[78:81]
	v_mfma_f32_16x16x32_bf16 v[70:73], v[170:173], v[210:213], v[70:73]
	v_mfma_f32_16x16x32_bf16 v[66:69], v[178:181], v[210:213], v[66:69]
	v_mfma_f32_16x16x32_bf16 v[118:121], v[174:177], v[190:193], v[118:121]
	v_mfma_f32_16x16x32_bf16 v[110:113], v[182:185], v[190:193], v[110:113]
	v_mfma_f32_16x16x32_bf16 v[102:105], v[174:177], v[198:201], v[102:105]
	v_mfma_f32_16x16x32_bf16 v[94:97], v[182:185], v[198:201], v[94:97]
	v_mfma_f32_16x16x32_bf16 v[86:89], v[174:177], v[206:209], v[86:89]
	v_mfma_f32_16x16x32_bf16 v[78:81], v[182:185], v[206:209], v[78:81]
	v_mfma_f32_16x16x32_bf16 v[70:73], v[174:177], v[214:217], v[70:73]
	v_mfma_f32_16x16x32_bf16 v[66:69], v[182:185], v[214:217], v[66:69]
	s_setprio 0
	s_barrier
	s_add_i32 s4, s67, s58
	s_mov_b32 m0, s4
	ds_read_b128 v[186:189], v152 offset:16384
	ds_read_b128 v[190:193], v146 offset:16384
	ds_read_b128 v[194:197], v152 offset:18432
	ds_read_b128 v[198:201], v146 offset:18432
	ds_read_b128 v[202:205], v152 offset:20480
	ds_read_b128 v[206:209], v146 offset:20480
	ds_read_b128 v[210:213], v152 offset:22528
	ds_read_b128 v[214:217], v146 offset:22528
	global_load_lds_dwordx4 v132, s[48:49]
	s_add_i32 m0, s4, 0x2000
	s_add_u32 s4, s48, 0x80000
	s_addc_u32 s5, s49, 0
	s_add_i32 s79, s68, s58
	global_load_lds_dwordx4 v136, s[48:49]
	s_mov_b32 m0, s79
	s_nop 0
	global_load_lds_dwordx4 v132, s[4:5]
	s_add_i32 m0, s79, 0x2000
	s_nop 0
	global_load_lds_dwordx4 v136, s[4:5]
	s_waitcnt vmcnt(6)
	s_waitcnt lgkmcnt(0)
	s_barrier
	s_setprio 1
	s_waitcnt lgkmcnt(0)
	v_mfma_f32_16x16x32_bf16 v[62:65], v[154:157], v[186:189], v[62:65]
	v_mfma_f32_16x16x32_bf16 v[58:61], v[162:165], v[186:189], v[58:61]
	v_mfma_f32_16x16x32_bf16 v[50:53], v[154:157], v[194:197], v[50:53]
	v_mfma_f32_16x16x32_bf16 v[42:45], v[162:165], v[194:197], v[42:45]
	v_mfma_f32_16x16x32_bf16 v[34:37], v[154:157], v[202:205], v[34:37]
	v_mfma_f32_16x16x32_bf16 v[26:29], v[162:165], v[202:205], v[26:29]
	v_mfma_f32_16x16x32_bf16 v[18:21], v[154:157], v[210:213], v[18:21]
	v_mfma_f32_16x16x32_bf16 v[10:13], v[162:165], v[210:213], v[10:13]
	v_mfma_f32_16x16x32_bf16 v[62:65], v[158:161], v[190:193], v[62:65]
	v_mfma_f32_16x16x32_bf16 v[58:61], v[166:169], v[190:193], v[58:61]
	v_mfma_f32_16x16x32_bf16 v[50:53], v[158:161], v[198:201], v[50:53]
	v_mfma_f32_16x16x32_bf16 v[42:45], v[166:169], v[198:201], v[42:45]
	v_mfma_f32_16x16x32_bf16 v[34:37], v[158:161], v[206:209], v[34:37]
	v_mfma_f32_16x16x32_bf16 v[26:29], v[166:169], v[206:209], v[26:29]
	v_mfma_f32_16x16x32_bf16 v[18:21], v[158:161], v[214:217], v[18:21]
	v_mfma_f32_16x16x32_bf16 v[10:13], v[166:169], v[214:217], v[10:13]
	s_setprio 0
	s_setprio 1
	v_mfma_f32_16x16x32_bf16 v[54:57], v[170:173], v[186:189], v[54:57]
	v_mfma_f32_16x16x32_bf16 v[46:49], v[178:181], v[186:189], v[46:49]
	v_mfma_f32_16x16x32_bf16 v[38:41], v[170:173], v[194:197], v[38:41]
	v_mfma_f32_16x16x32_bf16 v[30:33], v[178:181], v[194:197], v[30:33]
	v_mfma_f32_16x16x32_bf16 v[22:25], v[170:173], v[202:205], v[22:25]
	v_mfma_f32_16x16x32_bf16 v[14:17], v[178:181], v[202:205], v[14:17]
	v_mfma_f32_16x16x32_bf16 v[6:9], v[170:173], v[210:213], v[6:9]
	v_mfma_f32_16x16x32_bf16 v[2:5], v[178:181], v[210:213], v[2:5]
	v_mfma_f32_16x16x32_bf16 v[54:57], v[174:177], v[190:193], v[54:57]
	v_mfma_f32_16x16x32_bf16 v[46:49], v[182:185], v[190:193], v[46:49]
	v_mfma_f32_16x16x32_bf16 v[38:41], v[174:177], v[198:201], v[38:41]
	v_mfma_f32_16x16x32_bf16 v[30:33], v[182:185], v[198:201], v[30:33]
	v_mfma_f32_16x16x32_bf16 v[22:25], v[174:177], v[206:209], v[22:25]
	v_mfma_f32_16x16x32_bf16 v[14:17], v[182:185], v[206:209], v[14:17]
	v_mfma_f32_16x16x32_bf16 v[6:9], v[174:177], v[214:217], v[6:9]
	v_mfma_f32_16x16x32_bf16 v[2:5], v[182:185], v[214:217], v[2:5]
	s_setprio 0
	s_barrier
; #define PG8_STAGE(bufoff, gbase, voff) do { _Pragma("unroll") for (int _i = 0; _i < 2; ++_i) \
;         __builtin_amdgcn_global_load_lds((const unsigned*)((const char*)(gbase) + (voff)[_i]), (PG8_LAS unsigned*)(lds + (bufoff) + ldsw + _i * 8192), 16, 0, 0); } while (0)
; #define PG8_LDA(dst, b, h) do { _Pragma("unroll") for (int m = 0; m < 4; ++m) _Pragma("unroll") for (int k = 0; k < 2; ++k) dst[m][k] = *(const PG8_LAS bf16x8*)(lds + PG8_SA(b, h) + aoff + m * 2048 + k * 1024); } while (0)
; #define PG8_LDB(dst, b, h) do { _Pragma("unroll") for (int n = 0; n < 2; ++n) _Pragma("unroll") for (int k = 0; k < 2; ++k) dst[n][k] = *(const PG8_LAS bf16x8*)(lds + PG8_SB(b, h) + boff + n * 2048 + k * 1024); } while (0)
; #define PG8_MMA(ai, bj, At, Bt) do { __builtin_amdgcn_s_setprio(1); _Pragma("unroll") for (int m = 0; m < 4; ++m) _Pragma("unroll") for (int n = 0; n < 2; ++n) _Pragma("unroll") for (int k = 0; k < 2; ++k) \
;         acc[ai][bj][m][n] = __builtin_amdgcn_mfma_f32_16x16x32_bf16(Bt[n][k], At[m][k], acc[ai][bj][m][n], 0, 0, 0); __builtin_amdgcn_s_setprio(0); } while (0)
; #define PG8_WAIT_V(n) asm volatile("s_waitcnt vmcnt(" #n ")" ::: "memory")
; #define PG8_WAIT_L(n) asm volatile("s_waitcnt lgkmcnt(" #n ")" ::: "memory")
; #define PG8_BAR __builtin_amdgcn_s_barrier()
; template <class Epi, class Sched, bool ALIGN_EPI = false, bool SP2 = false>
; __device__ __forceinline__ void gemm_phase(PG8_LAS unsigned char* lds, const Gemm g, const Sched& S, const Epi& E) {
;     ...
;         for (int t = 0; t < nt; t += 2) {
;             const bool last = (t == nt - 2);
;             const char* a1 = cA + (size_t)(t + 1) * kstep;
;             const char* a2 = last ? nA : cA + (size_t)(t + 2) * kstep; const char* b2 = last ? nB : cB + (size_t)(t + 2) * kstep;
;             const char* a3 = a2 + kstep; const char* b3 = b2 + kstep;
;     ...
;             PG8_LDB(B0, 1, 0); PG8_LDB(B1, 1, 1); PG8_SCHED; PG8_LDA(At, 1, 0); PG8_STAGE(PG8_SA(0, 1), a2 + hstep, voffA);
;             PG8_WAIT_V(8); PG8_WAIT_L(0); PG8_BAR; PG8_MMA(0, 0, At, B0); PG8_MMA(0, 1, At, B1); PG8_BAR; PG8_SCHED;
;             PG8_LDA(At, 1, 1); PG8_STAGE(PG8_SB(1, 0), b3, voffB); PG8_STAGE(PG8_SB(1, 1), b3 + hstep, voffB); PG8_STAGE(PG8_SA(1, 0), a3, voffA);
;             PG8_WAIT_V(8); PG8_WAIT_L(0); PG8_BAR; PG8_MMA(1, 0, At, B0); PG8_MMA(1, 1, At, B1); PG8_BAR; PG8_SCHED;
	s_add_i32 s79, 0, 0x18000
	s_add_i32 s80, 0, 0x1c000
	ds_read_b128 v[154:157], v219
	ds_read_b128 v[158:161], v220
	ds_read_b128 v[162:165], v219 offset:2048
	ds_read_b128 v[166:169], v220 offset:2048
	ds_read_b128 v[170:173], v221
	ds_read_b128 v[174:177], v222
	ds_read_b128 v[178:181], v221 offset:2048
	ds_read_b128 v[182:185], v222 offset:2048
	s_add_u32 s4, s50, 0x80000
	s_addc_u32 s5, s51, 0
	s_mov_b32 m0, s39
	s_nop 0
	global_load_lds_dwordx4 v130, s[50:51]
	s_mov_b32 m0, s59
	s_nop 0
	global_load_lds_dwordx4 v134, s[50:51]
	s_mov_b32 m0, s60
	ds_read_b128 v[186:189], v152 offset:32768
	ds_read_b128 v[190:193], v146 offset:32768
	ds_read_b128 v[194:197], v152 offset:34816
	ds_read_b128 v[198:201], v146 offset:34816
	ds_read_b128 v[202:205], v152 offset:36864
	ds_read_b128 v[206:209], v146 offset:36864
	ds_read_b128 v[210:213], v152 offset:38912
	ds_read_b128 v[214:217], v146 offset:38912
	global_load_lds_dwordx4 v130, s[4:5]
	s_mov_b32 m0, s61
	s_nop 0
	global_load_lds_dwordx4 v134, s[4:5]
	s_waitcnt vmcnt(8)
	s_waitcnt lgkmcnt(0)
	s_barrier
	s_setprio 1
	s_waitcnt lgkmcnt(0)
	v_mfma_f32_16x16x32_bf16 v[126:129], v[154:157], v[186:189], v[126:129]
	v_mfma_f32_16x16x32_bf16 v[122:125], v[162:165], v[186:189], v[122:125]
	v_mfma_f32_16x16x32_bf16 v[114:117], v[154:157], v[194:197], v[114:117]
	v_mfma_f32_16x16x32_bf16 v[106:109], v[162:165], v[194:197], v[106:109]
	v_mfma_f32_16x16x32_bf16 v[98:101], v[154:157], v[202:205], v[98:101]
	v_mfma_f32_16x16x32_bf16 v[90:93], v[162:165], v[202:205], v[90:93]
	v_mfma_f32_16x16x32_bf16 v[82:85], v[154:157], v[210:213], v[82:85]
	v_mfma_f32_16x16x32_bf16 v[74:77], v[162:165], v[210:213], v[74:77]
	v_mfma_f32_16x16x32_bf16 v[126:129], v[158:161], v[190:193], v[126:129]
	v_mfma_f32_16x16x32_bf16 v[122:125], v[166:169], v[190:193], v[122:125]
	v_mfma_f32_16x16x32_bf16 v[114:117], v[158:161], v[198:201], v[114:117]
	v_mfma_f32_16x16x32_bf16 v[106:109], v[166:169], v[198:201], v[106:109]
	v_mfma_f32_16x16x32_bf16 v[98:101], v[158:161], v[206:209], v[98:101]
	v_mfma_f32_16x16x32_bf16 v[90:93], v[166:169], v[206:209], v[90:93]
	v_mfma_f32_16x16x32_bf16 v[82:85], v[158:161], v[214:217], v[82:85]
	v_mfma_f32_16x16x32_bf16 v[74:77], v[166:169], v[214:217], v[74:77]
	s_setprio 0
	s_setprio 1
	v_mfma_f32_16x16x32_bf16 v[118:121], v[170:173], v[186:189], v[118:121]
	v_mfma_f32_16x16x32_bf16 v[110:113], v[178:181], v[186:189], v[110:113]
	v_mfma_f32_16x16x32_bf16 v[102:105], v[170:173], v[194:197], v[102:105]
	v_mfma_f32_16x16x32_bf16 v[94:97], v[178:181], v[194:197], v[94:97]
	v_mfma_f32_16x16x32_bf16 v[86:89], v[170:173], v[202:205], v[86:89]
	v_mfma_f32_16x16x32_bf16 v[78:81], v[178:181], v[202:205], v[78:81]
	v_mfma_f32_16x16x32_bf16 v[70:73], v[170:173], v[210:213], v[70:73]
	v_mfma_f32_16x16x32_bf16 v[66:69], v[178:181], v[210:213], v[66:69]
	v_mfma_f32_16x16x32_bf16 v[118:121], v[174:177], v[190:193], v[118:121]
	v_mfma_f32_16x16x32_bf16 v[110:113], v[182:185], v[190:193], v[110:113]
	v_mfma_f32_16x16x32_bf16 v[102:105], v[174:177], v[198:201], v[102:105]
	v_mfma_f32_16x16x32_bf16 v[94:97], v[182:185], v[198:201], v[94:97]
	v_mfma_f32_16x16x32_bf16 v[86:89], v[174:177], v[206:209], v[86:89]
	v_mfma_f32_16x16x32_bf16 v[78:81], v[182:185], v[206:209], v[78:81]
	v_mfma_f32_16x16x32_bf16 v[70:73], v[174:177], v[214:217], v[70:73]
	v_mfma_f32_16x16x32_bf16 v[66:69], v[182:185], v[214:217], v[66:69]
	s_setprio 0
	s_barrier
	s_add_i32 s4, s79, s58
	s_add_i32 m0, s4, 0xffffff80
	ds_read_b128 v[186:189], v152 offset:49152
	ds_read_b128 v[190:193], v146 offset:49152
	ds_read_b128 v[194:197], v152 offset:51200
	ds_read_b128 v[198:201], v146 offset:51200
	ds_read_b128 v[202:205], v152 offset:53248
	ds_read_b128 v[206:209], v146 offset:53248
	ds_read_b128 v[210:213], v152 offset:55296
	ds_read_b128 v[214:217], v146 offset:55296
	global_load_lds_dwordx4 v132, s[48:49] offset:128
	s_add_i32 m0, s4, 0x1f80
	s_add_u32 s4, s48, 0x80080
	s_addc_u32 s5, s49, 0
	global_load_lds_dwordx4 v136, s[48:49] offset:128
	s_add_i32 s48, s80, s58
	s_mov_b32 m0, s48
	s_nop 0
	global_load_lds_dwordx4 v132, s[4:5]
	s_add_i32 m0, s48, 0x2000
	s_nop 0
	global_load_lds_dwordx4 v136, s[4:5]
	s_waitcnt vmcnt(6)
	s_waitcnt lgkmcnt(0)
	s_barrier
	s_setprio 1
	s_waitcnt lgkmcnt(0)
	v_mfma_f32_16x16x32_bf16 v[62:65], v[154:157], v[186:189], v[62:65]
	v_mfma_f32_16x16x32_bf16 v[58:61], v[162:165], v[186:189], v[58:61]
	v_mfma_f32_16x16x32_bf16 v[50:53], v[154:157], v[194:197], v[50:53]
	v_mfma_f32_16x16x32_bf16 v[42:45], v[162:165], v[194:197], v[42:45]
	v_mfma_f32_16x16x32_bf16 v[34:37], v[154:157], v[202:205], v[34:37]
	v_mfma_f32_16x16x32_bf16 v[26:29], v[162:165], v[202:205], v[26:29]
	v_mfma_f32_16x16x32_bf16 v[18:21], v[154:157], v[210:213], v[18:21]
	v_mfma_f32_16x16x32_bf16 v[10:13], v[162:165], v[210:213], v[10:13]
	v_mfma_f32_16x16x32_bf16 v[62:65], v[158:161], v[190:193], v[62:65]
	v_mfma_f32_16x16x32_bf16 v[58:61], v[166:169], v[190:193], v[58:61]
	v_mfma_f32_16x16x32_bf16 v[50:53], v[158:161], v[198:201], v[50:53]
	v_mfma_f32_16x16x32_bf16 v[42:45], v[166:169], v[198:201], v[42:45]
	v_mfma_f32_16x16x32_bf16 v[34:37], v[158:161], v[206:209], v[34:37]
	v_mfma_f32_16x16x32_bf16 v[26:29], v[166:169], v[206:209], v[26:29]
	v_mfma_f32_16x16x32_bf16 v[18:21], v[158:161], v[214:217], v[18:21]
	v_mfma_f32_16x16x32_bf16 v[10:13], v[166:169], v[214:217], v[10:13]
	s_setprio 0
	s_setprio 1
	v_mfma_f32_16x16x32_bf16 v[54:57], v[170:173], v[186:189], v[54:57]
	v_mfma_f32_16x16x32_bf16 v[46:49], v[178:181], v[186:189], v[46:49]
	v_mfma_f32_16x16x32_bf16 v[38:41], v[170:173], v[194:197], v[38:41]
	v_mfma_f32_16x16x32_bf16 v[30:33], v[178:181], v[194:197], v[30:33]
	v_mfma_f32_16x16x32_bf16 v[22:25], v[170:173], v[202:205], v[22:25]
	v_mfma_f32_16x16x32_bf16 v[14:17], v[178:181], v[202:205], v[14:17]
	v_mfma_f32_16x16x32_bf16 v[6:9], v[170:173], v[210:213], v[6:9]
	v_mfma_f32_16x16x32_bf16 v[2:5], v[178:181], v[210:213], v[2:5]
	v_mfma_f32_16x16x32_bf16 v[54:57], v[174:177], v[190:193], v[54:57]
	v_mfma_f32_16x16x32_bf16 v[46:49], v[182:185], v[190:193], v[46:49]
	v_mfma_f32_16x16x32_bf16 v[38:41], v[174:177], v[198:201], v[38:41]
	v_mfma_f32_16x16x32_bf16 v[30:33], v[182:185], v[198:201], v[30:33]
	v_mfma_f32_16x16x32_bf16 v[22:25], v[174:177], v[206:209], v[22:25]
	v_mfma_f32_16x16x32_bf16 v[14:17], v[182:185], v[206:209], v[14:17]
	v_mfma_f32_16x16x32_bf16 v[6:9], v[174:177], v[214:217], v[6:9]
	v_mfma_f32_16x16x32_bf16 v[2:5], v[182:185], v[214:217], v[2:5]
	s_setprio 0
	s_add_i32 s78, s78, 2
	s_add_u32 s40, s40, 0x100
	s_addc_u32 s41, s41, 0
	s_add_u32 s76, s76, 0x100
	s_addc_u32 s77, s77, 0
	s_cmp_gt_u32 s78, 29
	s_barrier
	s_cbranch_scc0 .LBB0_763
	s_and_b64 vcc, exec, s[20:21]
	s_cbranch_vccz .LBB0_766
	s_barrier

; #define PG8_STAGE(bufoff, gbase, voff) do { _Pragma("unroll") for (int _i = 0; _i < 2; ++_i) \
;         __builtin_amdgcn_global_load_lds((const unsigned*)((const char*)(gbase) + (voff)[_i]), (PG8_LAS unsigned*)(lds + (bufoff) + ldsw + _i * 8192), 16, 0, 0); } while (0)
; #define PG8_LDA(dst, b, h) do { _Pragma("unroll") for (int m = 0; m < 4; ++m) _Pragma("unroll") for (int k = 0; k < 2; ++k) dst[m][k] = *(const PG8_LAS bf16x8*)(lds + PG8_SA(b, h) + aoff + m * 2048 + k * 1024); } while (0)
; #define PG8_LDB(dst, b, h) do { _Pragma("unroll") for (int n = 0; n < 2; ++n) _Pragma("unroll") for (int k = 0; k < 2; ++k) dst[n][k] = *(const PG8_LAS bf16x8*)(lds + PG8_SB(b, h) + boff + n * 2048 + k * 1024); } while (0)
; #define PG8_WAIT_V(n) asm volatile("s_waitcnt vmcnt(" #n ")" ::: "memory")
; #define PG8_WAIT_L(n) asm volatile("s_waitcnt lgkmcnt(" #n ")" ::: "memory")
; #define PG8_BAR __builtin_amdgcn_s_barrier()
; #define PG8_SCHED __builtin_amdgcn_sched_barrier(0)
; template <class Epi, class Sched, bool ALIGN_EPI = false, bool SP2 = false>
; __device__ __forceinline__ void gemm_phase(PG8_LAS unsigned char* lds, const Gemm g, const Sched& S, const Epi& E) {
;     ...
;         const bool has_next = S.next(ui + 1, nxt);
;         const char* nA = has_next ? (const char*)g.A + (size_t)nxt.pm * tstep : cA; const char* nB = has_next ? (const char*)g.Bt + (size_t)nxt.pn * tstep : cB;
;         for (int t = 0; t < nt; t += 2) {
;             const bool last = (t == nt - 2);
;             const char* a1 = cA + (size_t)(t + 1) * kstep;
;             const char* a2 = last ? nA : cA + (size_t)(t + 2) * kstep; const char* b2 = last ? nB : cB + (size_t)(t + 2) * kstep;
;             const char* a3 = a2 + kstep; const char* b3 = b2 + kstep;
;             if (last && has_next) S.a_ready(nxt);
;             if constexpr (SP2) {
;             PG8_LDB(B0, 0, 0); PG8_LDB(B1, 0, 1); PG8_SCHED; PG8_LDA(At, 0, 0); PG8_STAGE(PG8_SA(1, 1), a1 + hstep, voffA);
;             PG8_WAIT_V(8); PG8_WAIT_L(0); PG8_BAR; PG8_MMA(0, 0, At, B0); PG8_MMA(0, 1, At, B1); PG8_BAR; PG8_SCHED;
;             PG8_LDA(At, 0, 1); PG8_STAGE(PG8_SB(0, 0), b2, voffB); PG8_STAGE(PG8_SB(0, 1), b2 + hstep, voffB); PG8_STAGE(PG8_SA(0, 0), a2, voffA);
;             PG8_WAIT_V(8); PG8_WAIT_L(0); PG8_BAR; PG8_MMA(1, 0, At, B0); PG8_MMA(1, 1, At, B1); PG8_BAR; PG8_SCHED;
.LBB0_913:
	ds_read_b128 v[156:159], v152
	ds_read_b128 v[160:163], v147
	ds_read_b128 v[164:167], v152 offset:2048
	ds_read_b128 v[168:171], v147 offset:2048
	ds_read_b128 v[172:175], v153
	ds_read_b128 v[176:179], v220
	ds_read_b128 v[180:183], v153 offset:2048
	ds_read_b128 v[184:187], v220 offset:2048
	s_add_u32 s4, s34, 0xfff80080
	s_addc_u32 s5, s35, -1
	s_cmp_eq_u32 s69, 28
	s_cselect_b32 s39, s25, s5
	s_cselect_b32 s38, s65, s4
	s_cselect_b32 s37, s23, s68
	s_cselect_b32 s36, s66, s67
	s_add_i32 m0, s53, 0x80
	s_nop 0
	global_load_lds_dwordx4 v136, s[4:5] offset:-128
	s_add_i32 m0, s58, 0x80
	s_nop 0
	global_load_lds_dwordx4 v132, s[4:5] offset:-128
	s_add_i32 m0, s31, 0xc000
	ds_read_b128 v[188:191], v154
	ds_read_b128 v[192:195], v146
	ds_read_b128 v[196:199], v154 offset:2048
	ds_read_b128 v[200:203], v146 offset:2048
	ds_read_b128 v[204:207], v154 offset:4096
	ds_read_b128 v[208:211], v146 offset:4096
	ds_read_b128 v[212:215], v154 offset:6144
	ds_read_b128 v[216:219], v146 offset:6144
	global_load_lds_dwordx4 v138, s[34:35]
	s_add_i32 m0, s31, 0xe000
	s_nop 0
	global_load_lds_dwordx4 v140, s[34:35]
	s_waitcnt vmcnt(8)
	s_waitcnt lgkmcnt(0)
	s_barrier
	s_setprio 1
	s_waitcnt lgkmcnt(0)
	v_mfma_f32_16x16x32_bf16 v[126:129], v[156:159], v[188:191], v[126:129]
	v_mfma_f32_16x16x32_bf16 v[122:125], v[164:167], v[188:191], v[122:125]
	v_mfma_f32_16x16x32_bf16 v[110:113], v[156:159], v[196:199], v[110:113]
	v_mfma_f32_16x16x32_bf16 v[106:109], v[164:167], v[196:199], v[106:109]
	v_mfma_f32_16x16x32_bf16 v[94:97], v[156:159], v[204:207], v[94:97]
	v_mfma_f32_16x16x32_bf16 v[90:93], v[164:167], v[204:207], v[90:93]
	v_mfma_f32_16x16x32_bf16 v[78:81], v[156:159], v[212:215], v[78:81]
	v_mfma_f32_16x16x32_bf16 v[74:77], v[164:167], v[212:215], v[74:77]
	v_mfma_f32_16x16x32_bf16 v[126:129], v[160:163], v[192:195], v[126:129]
	v_mfma_f32_16x16x32_bf16 v[122:125], v[168:171], v[192:195], v[122:125]
	v_mfma_f32_16x16x32_bf16 v[110:113], v[160:163], v[200:203], v[110:113]
	v_mfma_f32_16x16x32_bf16 v[106:109], v[168:171], v[200:203], v[106:109]
	v_mfma_f32_16x16x32_bf16 v[94:97], v[160:163], v[208:211], v[94:97]
	v_mfma_f32_16x16x32_bf16 v[90:93], v[168:171], v[208:211], v[90:93]
	v_mfma_f32_16x16x32_bf16 v[78:81], v[160:163], v[216:219], v[78:81]
	v_mfma_f32_16x16x32_bf16 v[74:77], v[168:171], v[216:219], v[74:77]
	s_setprio 0
	s_setprio 1
	v_mfma_f32_16x16x32_bf16 v[118:121], v[172:175], v[188:191], v[118:121]
	v_mfma_f32_16x16x32_bf16 v[114:117], v[180:183], v[188:191], v[114:117]
	v_mfma_f32_16x16x32_bf16 v[102:105], v[172:175], v[196:199], v[102:105]
	v_mfma_f32_16x16x32_bf16 v[98:101], v[180:183], v[196:199], v[98:101]
	v_mfma_f32_16x16x32_bf16 v[86:89], v[172:175], v[204:207], v[86:89]
	v_mfma_f32_16x16x32_bf16 v[82:85], v[180:183], v[204:207], v[82:85]
	v_mfma_f32_16x16x32_bf16 v[70:73], v[172:175], v[212:215], v[70:73]
	v_mfma_f32_16x16x32_bf16 v[66:69], v[180:183], v[212:215], v[66:69]
	v_mfma_f32_16x16x32_bf16 v[118:121], v[176:179], v[192:195], v[118:121]
	v_mfma_f32_16x16x32_bf16 v[114:117], v[184:187], v[192:195], v[114:117]
	v_mfma_f32_16x16x32_bf16 v[102:105], v[176:179], v[200:203], v[102:105]
	v_mfma_f32_16x16x32_bf16 v[98:101], v[184:187], v[200:203], v[98:101]
	v_mfma_f32_16x16x32_bf16 v[86:89], v[176:179], v[208:211], v[86:89]
	v_mfma_f32_16x16x32_bf16 v[82:85], v[184:187], v[208:211], v[82:85]
	v_mfma_f32_16x16x32_bf16 v[70:73], v[176:179], v[216:219], v[70:73]
	v_mfma_f32_16x16x32_bf16 v[66:69], v[184:187], v[216:219], v[66:69]
	s_setprio 0
	s_barrier
	s_add_i32 s4, s61, s40
	s_mov_b32 m0, s4
	ds_read_b128 v[188:191], v154 offset:16384
	ds_read_b128 v[192:195], v146 offset:16384
	ds_read_b128 v[196:199], v154 offset:18432
	ds_read_b128 v[200:203], v146 offset:18432
	ds_read_b128 v[204:207], v154 offset:20480
	ds_read_b128 v[208:211], v146 offset:20480
	ds_read_b128 v[212:215], v154 offset:22528
	ds_read_b128 v[216:219], v146 offset:22528
	global_load_lds_dwordx4 v134, s[36:37]
	s_add_i32 m0, s4, 0x2000
	s_add_u32 s4, s36, 0x80000
	s_addc_u32 s5, s37, 0
	s_add_i32 s70, s62, s40
	global_load_lds_dwordx4 v130, s[36:37]
	s_mov_b32 m0, s70
	s_nop 0
	global_load_lds_dwordx4 v134, s[4:5]
	s_add_i32 m0, s70, 0x2000
	s_nop 0
	global_load_lds_dwordx4 v130, s[4:5]
	s_waitcnt vmcnt(6)
	s_waitcnt lgkmcnt(0)
	s_barrier
	s_setprio 1
	s_waitcnt lgkmcnt(0)
	v_mfma_f32_16x16x32_bf16 v[62:65], v[156:159], v[188:191], v[62:65]
	v_mfma_f32_16x16x32_bf16 v[58:61], v[164:167], v[188:191], v[58:61]
	v_mfma_f32_16x16x32_bf16 v[46:49], v[156:159], v[196:199], v[46:49]
	v_mfma_f32_16x16x32_bf16 v[42:45], v[164:167], v[196:199], v[42:45]
	v_mfma_f32_16x16x32_bf16 v[30:33], v[156:159], v[204:207], v[30:33]
	v_mfma_f32_16x16x32_bf16 v[26:29], v[164:167], v[204:207], v[26:29]
	v_mfma_f32_16x16x32_bf16 v[14:17], v[156:159], v[212:215], v[14:17]
	v_mfma_f32_16x16x32_bf16 v[10:13], v[164:167], v[212:215], v[10:13]
	v_mfma_f32_16x16x32_bf16 v[62:65], v[160:163], v[192:195], v[62:65]
	v_mfma_f32_16x16x32_bf16 v[58:61], v[168:171], v[192:195], v[58:61]
	v_mfma_f32_16x16x32_bf16 v[46:49], v[160:163], v[200:203], v[46:49]
	v_mfma_f32_16x16x32_bf16 v[42:45], v[168:171], v[200:203], v[42:45]
	v_mfma_f32_16x16x32_bf16 v[30:33], v[160:163], v[208:211], v[30:33]
	v_mfma_f32_16x16x32_bf16 v[26:29], v[168:171], v[208:211], v[26:29]
	v_mfma_f32_16x16x32_bf16 v[14:17], v[160:163], v[216:219], v[14:17]
	v_mfma_f32_16x16x32_bf16 v[10:13], v[168:171], v[216:219], v[10:13]
	s_setprio 0
	s_setprio 1
	v_mfma_f32_16x16x32_bf16 v[54:57], v[172:175], v[188:191], v[54:57]
	v_mfma_f32_16x16x32_bf16 v[50:53], v[180:183], v[188:191], v[50:53]
	v_mfma_f32_16x16x32_bf16 v[38:41], v[172:175], v[196:199], v[38:41]
	v_mfma_f32_16x16x32_bf16 v[34:37], v[180:183], v[196:199], v[34:37]
	v_mfma_f32_16x16x32_bf16 v[22:25], v[172:175], v[204:207], v[22:25]
	v_mfma_f32_16x16x32_bf16 v[18:21], v[180:183], v[204:207], v[18:21]
	v_mfma_f32_16x16x32_bf16 v[6:9], v[172:175], v[212:215], v[6:9]
	v_mfma_f32_16x16x32_bf16 v[2:5], v[180:183], v[212:215], v[2:5]
	v_mfma_f32_16x16x32_bf16 v[54:57], v[176:179], v[192:195], v[54:57]
	v_mfma_f32_16x16x32_bf16 v[50:53], v[184:187], v[192:195], v[50:53]
	v_mfma_f32_16x16x32_bf16 v[38:41], v[176:179], v[200:203], v[38:41]
	v_mfma_f32_16x16x32_bf16 v[34:37], v[184:187], v[200:203], v[34:37]
	v_mfma_f32_16x16x32_bf16 v[22:25], v[176:179], v[208:211], v[22:25]
	v_mfma_f32_16x16x32_bf16 v[18:21], v[184:187], v[208:211], v[18:21]
	v_mfma_f32_16x16x32_bf16 v[6:9], v[176:179], v[216:219], v[6:9]
	v_mfma_f32_16x16x32_bf16 v[2:5], v[184:187], v[216:219], v[2:5]
	s_setprio 0
	s_barrier
; #define PG8_STAGE(bufoff, gbase, voff) do { _Pragma("unroll") for (int _i = 0; _i < 2; ++_i) \
;         __builtin_amdgcn_global_load_lds((const unsigned*)((const char*)(gbase) + (voff)[_i]), (PG8_LAS unsigned*)(lds + (bufoff) + ldsw + _i * 8192), 16, 0, 0); } while (0)
; #define PG8_LDA(dst, b, h) do { _Pragma("unroll") for (int m = 0; m < 4; ++m) _Pragma("unroll") for (int k = 0; k < 2; ++k) dst[m][k] = *(const PG8_LAS bf16x8*)(lds + PG8_SA(b, h) + aoff + m * 2048 + k * 1024); } while (0)
; #define PG8_LDB(dst, b, h) do { _Pragma("unroll") for (int n = 0; n < 2; ++n) _Pragma("unroll") for (int k = 0; k < 2; ++k) dst[n][k] = *(const PG8_LAS bf16x8*)(lds + PG8_SB(b, h) + boff + n * 2048 + k * 1024); } while (0)
; #define PG8_MMA(ai, bj, At, Bt) do { __builtin_amdgcn_s_setprio(1); _Pragma("unroll") for (int m = 0; m < 4; ++m) _Pragma("unroll") for (int n = 0; n < 2; ++n) _Pragma("unroll") for (int k = 0; k < 2; ++k) \
;         acc[ai][bj][m][n] = __builtin_amdgcn_mfma_f32_16x16x32_bf16(Bt[n][k], At[m][k], acc[ai][bj][m][n], 0, 0, 0); __builtin_amdgcn_s_setprio(0); } while (0)
; #define PG8_WAIT_V(n) asm volatile("s_waitcnt vmcnt(" #n ")" ::: "memory")
; #define PG8_WAIT_L(n) asm volatile("s_waitcnt lgkmcnt(" #n ")" ::: "memory")
; #define PG8_BAR __builtin_amdgcn_s_barrier()
; template <class Epi, class Sched, bool ALIGN_EPI = false, bool SP2 = false>
; __device__ __forceinline__ void gemm_phase(PG8_LAS unsigned char* lds, const Gemm g, const Sched& S, const Epi& E) {
;     ...
;         for (int t = 0; t < nt; t += 2) {
;             const bool last = (t == nt - 2);
;             const char* a1 = cA + (size_t)(t + 1) * kstep;
;             const char* a2 = last ? nA : cA + (size_t)(t + 2) * kstep; const char* b2 = last ? nB : cB + (size_t)(t + 2) * kstep;
;             const char* a3 = a2 + kstep; const char* b3 = b2 + kstep;
;     ...
;             PG8_LDB(B0, 1, 0); PG8_LDB(B1, 1, 1); PG8_SCHED; PG8_LDA(At, 1, 0); PG8_STAGE(PG8_SA(0, 1), a2 + hstep, voffA);
;             PG8_WAIT_V(8); PG8_WAIT_L(0); PG8_BAR; PG8_MMA(0, 0, At, B0); PG8_MMA(0, 1, At, B1); PG8_BAR; PG8_SCHED;
;             PG8_LDA(At, 1, 1); PG8_STAGE(PG8_SB(1, 0), b3, voffB); PG8_STAGE(PG8_SB(1, 1), b3 + hstep, voffB); PG8_STAGE(PG8_SA(1, 0), a3, voffA);
;             PG8_WAIT_V(8); PG8_WAIT_L(0); PG8_BAR; PG8_MMA(1, 0, At, B0); PG8_MMA(1, 1, At, B1); PG8_BAR; PG8_SCHED;
	s_add_i32 s70, 0, 0x18000
	s_add_i32 s71, 0, 0x1c000
	ds_read_b128 v[156:159], v221
	ds_read_b128 v[160:163], v222
	ds_read_b128 v[164:167], v221 offset:2048
	ds_read_b128 v[168:171], v222 offset:2048
	ds_read_b128 v[172:175], v223
	ds_read_b128 v[176:179], v224
	ds_read_b128 v[180:183], v223 offset:2048
	ds_read_b128 v[184:187], v224 offset:2048
	s_add_u32 s4, s38, 0x80000
	s_addc_u32 s5, s39, 0
	s_mov_b32 m0, s31
	s_nop 0
	global_load_lds_dwordx4 v136, s[38:39]
	s_mov_b32 m0, s49
	s_nop 0
	global_load_lds_dwordx4 v132, s[38:39]
	s_mov_b32 m0, s50
	ds_read_b128 v[188:191], v154 offset:32768
	ds_read_b128 v[192:195], v146 offset:32768
	ds_read_b128 v[196:199], v154 offset:34816
	ds_read_b128 v[200:203], v146 offset:34816
	ds_read_b128 v[204:207], v154 offset:36864
	ds_read_b128 v[208:211], v146 offset:36864
	ds_read_b128 v[212:215], v154 offset:38912
	ds_read_b128 v[216:219], v146 offset:38912
	global_load_lds_dwordx4 v136, s[4:5]
	s_mov_b32 m0, s51
	s_nop 0
	global_load_lds_dwordx4 v132, s[4:5]
	s_waitcnt vmcnt(8)
	s_waitcnt lgkmcnt(0)
	s_barrier
	s_setprio 1
	s_waitcnt lgkmcnt(0)
	v_mfma_f32_16x16x32_bf16 v[126:129], v[156:159], v[188:191], v[126:129]
	v_mfma_f32_16x16x32_bf16 v[122:125], v[164:167], v[188:191], v[122:125]
	v_mfma_f32_16x16x32_bf16 v[110:113], v[156:159], v[196:199], v[110:113]
	v_mfma_f32_16x16x32_bf16 v[106:109], v[164:167], v[196:199], v[106:109]
	v_mfma_f32_16x16x32_bf16 v[94:97], v[156:159], v[204:207], v[94:97]
	v_mfma_f32_16x16x32_bf16 v[90:93], v[164:167], v[204:207], v[90:93]
	v_mfma_f32_16x16x32_bf16 v[78:81], v[156:159], v[212:215], v[78:81]
	v_mfma_f32_16x16x32_bf16 v[74:77], v[164:167], v[212:215], v[74:77]
	v_mfma_f32_16x16x32_bf16 v[126:129], v[160:163], v[192:195], v[126:129]
	v_mfma_f32_16x16x32_bf16 v[122:125], v[168:171], v[192:195], v[122:125]
	v_mfma_f32_16x16x32_bf16 v[110:113], v[160:163], v[200:203], v[110:113]
	v_mfma_f32_16x16x32_bf16 v[106:109], v[168:171], v[200:203], v[106:109]
	v_mfma_f32_16x16x32_bf16 v[94:97], v[160:163], v[208:211], v[94:97]
	v_mfma_f32_16x16x32_bf16 v[90:93], v[168:171], v[208:211], v[90:93]
	v_mfma_f32_16x16x32_bf16 v[78:81], v[160:163], v[216:219], v[78:81]
	v_mfma_f32_16x16x32_bf16 v[74:77], v[168:171], v[216:219], v[74:77]
	s_setprio 0
	s_setprio 1
	v_mfma_f32_16x16x32_bf16 v[118:121], v[172:175], v[188:191], v[118:121]
	v_mfma_f32_16x16x32_bf16 v[114:117], v[180:183], v[188:191], v[114:117]
	v_mfma_f32_16x16x32_bf16 v[102:105], v[172:175], v[196:199], v[102:105]
	v_mfma_f32_16x16x32_bf16 v[98:101], v[180:183], v[196:199], v[98:101]
	v_mfma_f32_16x16x32_bf16 v[86:89], v[172:175], v[204:207], v[86:89]
	v_mfma_f32_16x16x32_bf16 v[82:85], v[180:183], v[204:207], v[82:85]
	v_mfma_f32_16x16x32_bf16 v[70:73], v[172:175], v[212:215], v[70:73]
	v_mfma_f32_16x16x32_bf16 v[66:69], v[180:183], v[212:215], v[66:69]
	v_mfma_f32_16x16x32_bf16 v[118:121], v[176:179], v[192:195], v[118:121]
	v_mfma_f32_16x16x32_bf16 v[114:117], v[184:187], v[192:195], v[114:117]
	v_mfma_f32_16x16x32_bf16 v[102:105], v[176:179], v[200:203], v[102:105]
	v_mfma_f32_16x16x32_bf16 v[98:101], v[184:187], v[200:203], v[98:101]
	v_mfma_f32_16x16x32_bf16 v[86:89], v[176:179], v[208:211], v[86:89]
	v_mfma_f32_16x16x32_bf16 v[82:85], v[184:187], v[208:211], v[82:85]
	v_mfma_f32_16x16x32_bf16 v[70:73], v[176:179], v[216:219], v[70:73]
	v_mfma_f32_16x16x32_bf16 v[66:69], v[184:187], v[216:219], v[66:69]
	s_setprio 0
	s_barrier
	s_add_i32 s4, s70, s40
	s_add_i32 m0, s4, 0xffffff80
	ds_read_b128 v[188:191], v154 offset:49152
	ds_read_b128 v[192:195], v146 offset:49152
	ds_read_b128 v[196:199], v154 offset:51200
	ds_read_b128 v[200:203], v146 offset:51200
	ds_read_b128 v[204:207], v154 offset:53248
	ds_read_b128 v[208:211], v146 offset:53248
	ds_read_b128 v[212:215], v154 offset:55296
	ds_read_b128 v[216:219], v146 offset:55296
	global_load_lds_dwordx4 v134, s[36:37] offset:128
	s_add_i32 m0, s4, 0x1f80
	s_add_u32 s4, s36, 0x80080
	s_addc_u32 s5, s37, 0
	global_load_lds_dwordx4 v130, s[36:37] offset:128
	s_add_i32 s36, s71, s40
	s_mov_b32 m0, s36
	s_nop 0
	global_load_lds_dwordx4 v134, s[4:5]
	s_add_i32 m0, s36, 0x2000
	s_nop 0
	global_load_lds_dwordx4 v130, s[4:5]
	s_waitcnt vmcnt(6)
	s_waitcnt lgkmcnt(0)
	s_barrier
	s_setprio 1
	s_waitcnt lgkmcnt(0)
	v_mfma_f32_16x16x32_bf16 v[62:65], v[156:159], v[188:191], v[62:65]
	v_mfma_f32_16x16x32_bf16 v[58:61], v[164:167], v[188:191], v[58:61]
	v_mfma_f32_16x16x32_bf16 v[46:49], v[156:159], v[196:199], v[46:49]
	v_mfma_f32_16x16x32_bf16 v[42:45], v[164:167], v[196:199], v[42:45]
	v_mfma_f32_16x16x32_bf16 v[30:33], v[156:159], v[204:207], v[30:33]
	v_mfma_f32_16x16x32_bf16 v[26:29], v[164:167], v[204:207], v[26:29]
	v_mfma_f32_16x16x32_bf16 v[14:17], v[156:159], v[212:215], v[14:17]
	v_mfma_f32_16x16x32_bf16 v[10:13], v[164:167], v[212:215], v[10:13]
	v_mfma_f32_16x16x32_bf16 v[62:65], v[160:163], v[192:195], v[62:65]
	v_mfma_f32_16x16x32_bf16 v[58:61], v[168:171], v[192:195], v[58:61]
	v_mfma_f32_16x16x32_bf16 v[46:49], v[160:163], v[200:203], v[46:49]
	v_mfma_f32_16x16x32_bf16 v[42:45], v[168:171], v[200:203], v[42:45]
	v_mfma_f32_16x16x32_bf16 v[30:33], v[160:163], v[208:211], v[30:33]
	v_mfma_f32_16x16x32_bf16 v[26:29], v[168:171], v[208:211], v[26:29]
	v_mfma_f32_16x16x32_bf16 v[14:17], v[160:163], v[216:219], v[14:17]
	v_mfma_f32_16x16x32_bf16 v[10:13], v[168:171], v[216:219], v[10:13]
	s_setprio 0
	s_setprio 1
	v_mfma_f32_16x16x32_bf16 v[54:57], v[172:175], v[188:191], v[54:57]
	v_mfma_f32_16x16x32_bf16 v[50:53], v[180:183], v[188:191], v[50:53]
	v_mfma_f32_16x16x32_bf16 v[38:41], v[172:175], v[196:199], v[38:41]
	v_mfma_f32_16x16x32_bf16 v[34:37], v[180:183], v[196:199], v[34:37]
	v_mfma_f32_16x16x32_bf16 v[22:25], v[172:175], v[204:207], v[22:25]
	v_mfma_f32_16x16x32_bf16 v[18:21], v[180:183], v[204:207], v[18:21]
	v_mfma_f32_16x16x32_bf16 v[6:9], v[172:175], v[212:215], v[6:9]
	v_mfma_f32_16x16x32_bf16 v[2:5], v[180:183], v[212:215], v[2:5]
	v_mfma_f32_16x16x32_bf16 v[54:57], v[176:179], v[192:195], v[54:57]
	v_mfma_f32_16x16x32_bf16 v[50:53], v[184:187], v[192:195], v[50:53]
	v_mfma_f32_16x16x32_bf16 v[38:41], v[176:179], v[200:203], v[38:41]
	v_mfma_f32_16x16x32_bf16 v[34:37], v[184:187], v[200:203], v[34:37]
	v_mfma_f32_16x16x32_bf16 v[22:25], v[176:179], v[208:211], v[22:25]
	v_mfma_f32_16x16x32_bf16 v[18:21], v[184:187], v[208:211], v[18:21]
	v_mfma_f32_16x16x32_bf16 v[6:9], v[176:179], v[216:219], v[6:9]
	v_mfma_f32_16x16x32_bf16 v[2:5], v[184:187], v[216:219], v[2:5]
	s_setprio 0
	s_add_i32 s69, s69, 2
	s_add_u32 s34, s34, 0x100
	s_addc_u32 s35, s35, 0
	s_add_u32 s67, s67, 0x100
	s_addc_u32 s68, s68, 0
	s_cmp_gt_u32 s69, 29
	s_barrier
	s_cbranch_scc0 .LBB0_913
	s_and_b64 vcc, exec, s[20:21]
	s_cbranch_vccz .LBB0_916
	s_barrier

; #define PG8_STAGE(bufoff, gbase, voff) do { _Pragma("unroll") for (int _i = 0; _i < 2; ++_i) \
;         __builtin_amdgcn_global_load_lds((const unsigned*)((const char*)(gbase) + (voff)[_i]), (PG8_LAS unsigned*)(lds + (bufoff) + ldsw + _i * 8192), 16, 0, 0); } while (0)
; #define PG8_LDA(dst, b, h) do { _Pragma("unroll") for (int m = 0; m < 4; ++m) _Pragma("unroll") for (int k = 0; k < 2; ++k) dst[m][k] = *(const PG8_LAS bf16x8*)(lds + PG8_SA(b, h) + aoff + m * 2048 + k * 1024); } while (0)
; #define PG8_LDB(dst, b, h) do { _Pragma("unroll") for (int n = 0; n < 2; ++n) _Pragma("unroll") for (int k = 0; k < 2; ++k) dst[n][k] = *(const PG8_LAS bf16x8*)(lds + PG8_SB(b, h) + boff + n * 2048 + k * 1024); } while (0)
; #define PG8_WAIT_V(n) asm volatile("s_waitcnt vmcnt(" #n ")" ::: "memory")
; #define PG8_WAIT_L(n) asm volatile("s_waitcnt lgkmcnt(" #n ")" ::: "memory")
; #define PG8_BAR __builtin_amdgcn_s_barrier()
; #define PG8_SCHED __builtin_amdgcn_sched_barrier(0)
; template <class Epi, class Sched, bool ALIGN_EPI = false, bool SP2 = false>
; __device__ __forceinline__ void gemm_phase(PG8_LAS unsigned char* lds, const Gemm g, const Sched& S, const Epi& E) {
;     ...
;         const bool has_next = S.next(ui + 1, nxt);
;         const char* nA = has_next ? (const char*)g.A + (size_t)nxt.pm * tstep : cA; const char* nB = has_next ? (const char*)g.Bt + (size_t)nxt.pn * tstep : cB;
;         for (int t = 0; t < nt; t += 2) {
;             const bool last = (t == nt - 2);
;             const char* a1 = cA + (size_t)(t + 1) * kstep;
;             const char* a2 = last ? nA : cA + (size_t)(t + 2) * kstep; const char* b2 = last ? nB : cB + (size_t)(t + 2) * kstep;
;             const char* a3 = a2 + kstep; const char* b3 = b2 + kstep;
;             if (last && has_next) S.a_ready(nxt);
;             if constexpr (SP2) {
;             PG8_LDB(B0, 0, 0); PG8_LDB(B1, 0, 1); PG8_SCHED; PG8_LDA(At, 0, 0); PG8_STAGE(PG8_SA(1, 1), a1 + hstep, voffA);
;             PG8_WAIT_V(8); PG8_WAIT_L(0); PG8_BAR; PG8_MMA(0, 0, At, B0); PG8_MMA(0, 1, At, B1); PG8_BAR; PG8_SCHED;
;             PG8_LDA(At, 0, 1); PG8_STAGE(PG8_SB(0, 0), b2, voffB); PG8_STAGE(PG8_SB(0, 1), b2 + hstep, voffB); PG8_STAGE(PG8_SA(0, 0), a2, voffA);
;             PG8_WAIT_V(8); PG8_WAIT_L(0); PG8_BAR; PG8_MMA(1, 0, At, B0); PG8_MMA(1, 1, At, B1); PG8_BAR; PG8_SCHED;
.LBB0_1017:
	ds_read_b128 v[154:157], v150
	ds_read_b128 v[158:161], v147
	ds_read_b128 v[162:165], v150 offset:2048
	ds_read_b128 v[166:169], v147 offset:2048
	ds_read_b128 v[170:173], v151
	ds_read_b128 v[174:177], v218
	ds_read_b128 v[178:181], v151 offset:2048
	ds_read_b128 v[182:185], v218 offset:2048
	s_add_u32 s34, s30, 0x100
	s_addc_u32 s35, s31, 0
	s_cmpk_eq_i32 s74, 0x54
	s_cselect_b32 s39, s9, s35
	s_cselect_b32 s38, s8, s34
	s_cselect_b32 s37, s29, s73
	s_cselect_b32 s36, s28, s72
	s_add_i32 m0, s58, 0x80
	s_nop 0
	global_load_lds_dwordx4 v130, s[34:35] offset:-128
	s_add_i32 m0, s59, 0x80
	s_nop 0
	global_load_lds_dwordx4 v134, s[34:35] offset:-128
	s_add_i32 m0, s49, 0xc000
	ds_read_b128 v[186:189], v152
	ds_read_b128 v[190:193], v146
	ds_read_b128 v[194:197], v152 offset:2048
	ds_read_b128 v[198:201], v146 offset:2048
	ds_read_b128 v[202:205], v152 offset:4096
	ds_read_b128 v[206:209], v146 offset:4096
	ds_read_b128 v[210:213], v152 offset:6144
	ds_read_b128 v[214:217], v146 offset:6144
	global_load_lds_dwordx4 v138, s[30:31]
	s_add_i32 m0, s49, 0xe000
	s_nop 0
	global_load_lds_dwordx4 v140, s[30:31]
	s_waitcnt vmcnt(8)
	s_waitcnt lgkmcnt(0)
	s_barrier
	s_setprio 1
	s_waitcnt lgkmcnt(0)
	v_mfma_f32_16x16x32_bf16 v[126:129], v[154:157], v[186:189], v[126:129]
	v_mfma_f32_16x16x32_bf16 v[122:125], v[162:165], v[186:189], v[122:125]
	v_mfma_f32_16x16x32_bf16 v[114:117], v[154:157], v[194:197], v[114:117]
	v_mfma_f32_16x16x32_bf16 v[106:109], v[162:165], v[194:197], v[106:109]
	v_mfma_f32_16x16x32_bf16 v[98:101], v[154:157], v[202:205], v[98:101]
	v_mfma_f32_16x16x32_bf16 v[90:93], v[162:165], v[202:205], v[90:93]
	v_mfma_f32_16x16x32_bf16 v[82:85], v[154:157], v[210:213], v[82:85]
	v_mfma_f32_16x16x32_bf16 v[74:77], v[162:165], v[210:213], v[74:77]
	v_mfma_f32_16x16x32_bf16 v[126:129], v[158:161], v[190:193], v[126:129]
	v_mfma_f32_16x16x32_bf16 v[122:125], v[166:169], v[190:193], v[122:125]
	v_mfma_f32_16x16x32_bf16 v[114:117], v[158:161], v[198:201], v[114:117]
	v_mfma_f32_16x16x32_bf16 v[106:109], v[166:169], v[198:201], v[106:109]
	v_mfma_f32_16x16x32_bf16 v[98:101], v[158:161], v[206:209], v[98:101]
	v_mfma_f32_16x16x32_bf16 v[90:93], v[166:169], v[206:209], v[90:93]
	v_mfma_f32_16x16x32_bf16 v[82:85], v[158:161], v[214:217], v[82:85]
	v_mfma_f32_16x16x32_bf16 v[74:77], v[166:169], v[214:217], v[74:77]
	s_setprio 0
	s_setprio 1
	v_mfma_f32_16x16x32_bf16 v[118:121], v[170:173], v[186:189], v[118:121]
	v_mfma_f32_16x16x32_bf16 v[110:113], v[178:181], v[186:189], v[110:113]
	v_mfma_f32_16x16x32_bf16 v[102:105], v[170:173], v[194:197], v[102:105]
	v_mfma_f32_16x16x32_bf16 v[94:97], v[178:181], v[194:197], v[94:97]
	v_mfma_f32_16x16x32_bf16 v[86:89], v[170:173], v[202:205], v[86:89]
	v_mfma_f32_16x16x32_bf16 v[78:81], v[178:181], v[202:205], v[78:81]
	v_mfma_f32_16x16x32_bf16 v[70:73], v[170:173], v[210:213], v[70:73]
	v_mfma_f32_16x16x32_bf16 v[66:69], v[178:181], v[210:213], v[66:69]
	v_mfma_f32_16x16x32_bf16 v[118:121], v[174:177], v[190:193], v[118:121]
	v_mfma_f32_16x16x32_bf16 v[110:113], v[182:185], v[190:193], v[110:113]
	v_mfma_f32_16x16x32_bf16 v[102:105], v[174:177], v[198:201], v[102:105]
	v_mfma_f32_16x16x32_bf16 v[94:97], v[182:185], v[198:201], v[94:97]
	v_mfma_f32_16x16x32_bf16 v[86:89], v[174:177], v[206:209], v[86:89]
	v_mfma_f32_16x16x32_bf16 v[78:81], v[182:185], v[206:209], v[78:81]
	v_mfma_f32_16x16x32_bf16 v[70:73], v[174:177], v[214:217], v[70:73]
	v_mfma_f32_16x16x32_bf16 v[66:69], v[182:185], v[214:217], v[66:69]
	s_setprio 0
	s_barrier
	s_add_i32 s4, s62, s48
	s_mov_b32 m0, s4
	ds_read_b128 v[186:189], v152 offset:16384
	ds_read_b128 v[190:193], v146 offset:16384
	ds_read_b128 v[194:197], v152 offset:18432
	ds_read_b128 v[198:201], v146 offset:18432
	ds_read_b128 v[202:205], v152 offset:20480
	ds_read_b128 v[206:209], v146 offset:20480
	ds_read_b128 v[210:213], v152 offset:22528
	ds_read_b128 v[214:217], v146 offset:22528
	global_load_lds_dwordx4 v132, s[36:37]
	s_add_i32 m0, s4, 0x2000
	s_add_u32 s4, s36, 0x160000
	s_addc_u32 s5, s37, 0
	s_add_i32 s30, s63, s48
	global_load_lds_dwordx4 v136, s[36:37]
	s_mov_b32 m0, s30
	s_nop 0
	global_load_lds_dwordx4 v132, s[4:5]
	s_add_i32 m0, s30, 0x2000
	s_nop 0
	global_load_lds_dwordx4 v136, s[4:5]
	s_waitcnt vmcnt(6)
	s_waitcnt lgkmcnt(0)
	s_barrier
	s_setprio 1
	s_waitcnt lgkmcnt(0)
	v_mfma_f32_16x16x32_bf16 v[62:65], v[154:157], v[186:189], v[62:65]
	v_mfma_f32_16x16x32_bf16 v[58:61], v[162:165], v[186:189], v[58:61]
	v_mfma_f32_16x16x32_bf16 v[50:53], v[154:157], v[194:197], v[50:53]
	v_mfma_f32_16x16x32_bf16 v[42:45], v[162:165], v[194:197], v[42:45]
	v_mfma_f32_16x16x32_bf16 v[34:37], v[154:157], v[202:205], v[34:37]
	v_mfma_f32_16x16x32_bf16 v[26:29], v[162:165], v[202:205], v[26:29]
	v_mfma_f32_16x16x32_bf16 v[18:21], v[154:157], v[210:213], v[18:21]
	v_mfma_f32_16x16x32_bf16 v[10:13], v[162:165], v[210:213], v[10:13]
	v_mfma_f32_16x16x32_bf16 v[62:65], v[158:161], v[190:193], v[62:65]
	v_mfma_f32_16x16x32_bf16 v[58:61], v[166:169], v[190:193], v[58:61]
	v_mfma_f32_16x16x32_bf16 v[50:53], v[158:161], v[198:201], v[50:53]
	v_mfma_f32_16x16x32_bf16 v[42:45], v[166:169], v[198:201], v[42:45]
	v_mfma_f32_16x16x32_bf16 v[34:37], v[158:161], v[206:209], v[34:37]
	v_mfma_f32_16x16x32_bf16 v[26:29], v[166:169], v[206:209], v[26:29]
	v_mfma_f32_16x16x32_bf16 v[18:21], v[158:161], v[214:217], v[18:21]
	v_mfma_f32_16x16x32_bf16 v[10:13], v[166:169], v[214:217], v[10:13]
	s_setprio 0
	s_setprio 1
	v_mfma_f32_16x16x32_bf16 v[54:57], v[170:173], v[186:189], v[54:57]
	v_mfma_f32_16x16x32_bf16 v[46:49], v[178:181], v[186:189], v[46:49]
	v_mfma_f32_16x16x32_bf16 v[38:41], v[170:173], v[194:197], v[38:41]
	v_mfma_f32_16x16x32_bf16 v[30:33], v[178:181], v[194:197], v[30:33]
	v_mfma_f32_16x16x32_bf16 v[22:25], v[170:173], v[202:205], v[22:25]
	v_mfma_f32_16x16x32_bf16 v[14:17], v[178:181], v[202:205], v[14:17]
	v_mfma_f32_16x16x32_bf16 v[6:9], v[170:173], v[210:213], v[6:9]
	v_mfma_f32_16x16x32_bf16 v[2:5], v[178:181], v[210:213], v[2:5]
	v_mfma_f32_16x16x32_bf16 v[54:57], v[174:177], v[190:193], v[54:57]
	v_mfma_f32_16x16x32_bf16 v[46:49], v[182:185], v[190:193], v[46:49]
	v_mfma_f32_16x16x32_bf16 v[38:41], v[174:177], v[198:201], v[38:41]
	v_mfma_f32_16x16x32_bf16 v[30:33], v[182:185], v[198:201], v[30:33]
	v_mfma_f32_16x16x32_bf16 v[22:25], v[174:177], v[206:209], v[22:25]
	v_mfma_f32_16x16x32_bf16 v[14:17], v[182:185], v[206:209], v[14:17]
	v_mfma_f32_16x16x32_bf16 v[6:9], v[174:177], v[214:217], v[6:9]
	v_mfma_f32_16x16x32_bf16 v[2:5], v[182:185], v[214:217], v[2:5]
	s_setprio 0
	s_barrier
; #define PG8_STAGE(bufoff, gbase, voff) do { _Pragma("unroll") for (int _i = 0; _i < 2; ++_i) \
;         __builtin_amdgcn_global_load_lds((const unsigned*)((const char*)(gbase) + (voff)[_i]), (PG8_LAS unsigned*)(lds + (bufoff) + ldsw + _i * 8192), 16, 0, 0); } while (0)
; #define PG8_LDA(dst, b, h) do { _Pragma("unroll") for (int m = 0; m < 4; ++m) _Pragma("unroll") for (int k = 0; k < 2; ++k) dst[m][k] = *(const PG8_LAS bf16x8*)(lds + PG8_SA(b, h) + aoff + m * 2048 + k * 1024); } while (0)
; #define PG8_LDB(dst, b, h) do { _Pragma("unroll") for (int n = 0; n < 2; ++n) _Pragma("unroll") for (int k = 0; k < 2; ++k) dst[n][k] = *(const PG8_LAS bf16x8*)(lds + PG8_SB(b, h) + boff + n * 2048 + k * 1024); } while (0)
; #define PG8_MMA(ai, bj, At, Bt) do { __builtin_amdgcn_s_setprio(1); _Pragma("unroll") for (int m = 0; m < 4; ++m) _Pragma("unroll") for (int n = 0; n < 2; ++n) _Pragma("unroll") for (int k = 0; k < 2; ++k) \
;         acc[ai][bj][m][n] = __builtin_amdgcn_mfma_f32_16x16x32_bf16(Bt[n][k], At[m][k], acc[ai][bj][m][n], 0, 0, 0); __builtin_amdgcn_s_setprio(0); } while (0)
; #define PG8_WAIT_V(n) asm volatile("s_waitcnt vmcnt(" #n ")" ::: "memory")
; #define PG8_WAIT_L(n) asm volatile("s_waitcnt lgkmcnt(" #n ")" ::: "memory")
; #define PG8_BAR __builtin_amdgcn_s_barrier()
; template <class Epi, class Sched, bool ALIGN_EPI = false, bool SP2 = false>
; __device__ __forceinline__ void gemm_phase(PG8_LAS unsigned char* lds, const Gemm g, const Sched& S, const Epi& E) {
;     ...
;         for (int t = 0; t < nt; t += 2) {
;             const bool last = (t == nt - 2);
;             const char* a1 = cA + (size_t)(t + 1) * kstep;
;             const char* a2 = last ? nA : cA + (size_t)(t + 2) * kstep; const char* b2 = last ? nB : cB + (size_t)(t + 2) * kstep;
;             const char* a3 = a2 + kstep; const char* b3 = b2 + kstep;
;     ...
;             PG8_LDB(B0, 1, 0); PG8_LDB(B1, 1, 1); PG8_SCHED; PG8_LDA(At, 1, 0); PG8_STAGE(PG8_SA(0, 1), a2 + hstep, voffA);
;             PG8_WAIT_V(8); PG8_WAIT_L(0); PG8_BAR; PG8_MMA(0, 0, At, B0); PG8_MMA(0, 1, At, B1); PG8_BAR; PG8_SCHED;
;             PG8_LDA(At, 1, 1); PG8_STAGE(PG8_SB(1, 0), b3, voffB); PG8_STAGE(PG8_SB(1, 1), b3 + hstep, voffB); PG8_STAGE(PG8_SA(1, 0), a3, voffA);
;             PG8_WAIT_V(8); PG8_WAIT_L(0); PG8_BAR; PG8_MMA(1, 0, At, B0); PG8_MMA(1, 1, At, B1); PG8_BAR; PG8_SCHED;
	s_add_i32 s30, 0, 0x18000
	s_add_i32 s31, 0, 0x1c000
	ds_read_b128 v[154:157], v219
	ds_read_b128 v[158:161], v220
	ds_read_b128 v[162:165], v219 offset:2048
	ds_read_b128 v[166:169], v220 offset:2048
	ds_read_b128 v[170:173], v221
	ds_read_b128 v[174:177], v222
	ds_read_b128 v[178:181], v221 offset:2048
	ds_read_b128 v[182:185], v222 offset:2048
	s_add_u32 s4, s38, 0x160000
	s_addc_u32 s5, s39, 0
	s_mov_b32 m0, s49
	s_nop 0
	global_load_lds_dwordx4 v130, s[38:39]
	s_mov_b32 m0, s50
	s_nop 0
	global_load_lds_dwordx4 v134, s[38:39]
	s_mov_b32 m0, s51
	ds_read_b128 v[186:189], v152 offset:32768
	ds_read_b128 v[190:193], v146 offset:32768
	ds_read_b128 v[194:197], v152 offset:34816
	ds_read_b128 v[198:201], v146 offset:34816
	ds_read_b128 v[202:205], v152 offset:36864
	ds_read_b128 v[206:209], v146 offset:36864
	ds_read_b128 v[210:213], v152 offset:38912
	ds_read_b128 v[214:217], v146 offset:38912
	global_load_lds_dwordx4 v130, s[4:5]
	s_mov_b32 m0, s52
	s_nop 0
	global_load_lds_dwordx4 v134, s[4:5]
	s_waitcnt vmcnt(8)
	s_waitcnt lgkmcnt(0)
	s_barrier
	s_setprio 1
	s_waitcnt lgkmcnt(0)
	v_mfma_f32_16x16x32_bf16 v[126:129], v[154:157], v[186:189], v[126:129]
	v_mfma_f32_16x16x32_bf16 v[122:125], v[162:165], v[186:189], v[122:125]
	v_mfma_f32_16x16x32_bf16 v[114:117], v[154:157], v[194:197], v[114:117]
	v_mfma_f32_16x16x32_bf16 v[106:109], v[162:165], v[194:197], v[106:109]
	v_mfma_f32_16x16x32_bf16 v[98:101], v[154:157], v[202:205], v[98:101]
	v_mfma_f32_16x16x32_bf16 v[90:93], v[162:165], v[202:205], v[90:93]
	v_mfma_f32_16x16x32_bf16 v[82:85], v[154:157], v[210:213], v[82:85]
	v_mfma_f32_16x16x32_bf16 v[74:77], v[162:165], v[210:213], v[74:77]
	v_mfma_f32_16x16x32_bf16 v[126:129], v[158:161], v[190:193], v[126:129]
	v_mfma_f32_16x16x32_bf16 v[122:125], v[166:169], v[190:193], v[122:125]
	v_mfma_f32_16x16x32_bf16 v[114:117], v[158:161], v[198:201], v[114:117]
	v_mfma_f32_16x16x32_bf16 v[106:109], v[166:169], v[198:201], v[106:109]
	v_mfma_f32_16x16x32_bf16 v[98:101], v[158:161], v[206:209], v[98:101]
	v_mfma_f32_16x16x32_bf16 v[90:93], v[166:169], v[206:209], v[90:93]
	v_mfma_f32_16x16x32_bf16 v[82:85], v[158:161], v[214:217], v[82:85]
	v_mfma_f32_16x16x32_bf16 v[74:77], v[166:169], v[214:217], v[74:77]
	s_setprio 0
	s_setprio 1
	v_mfma_f32_16x16x32_bf16 v[118:121], v[170:173], v[186:189], v[118:121]
	v_mfma_f32_16x16x32_bf16 v[110:113], v[178:181], v[186:189], v[110:113]
	v_mfma_f32_16x16x32_bf16 v[102:105], v[170:173], v[194:197], v[102:105]
	v_mfma_f32_16x16x32_bf16 v[94:97], v[178:181], v[194:197], v[94:97]
	v_mfma_f32_16x16x32_bf16 v[86:89], v[170:173], v[202:205], v[86:89]
	v_mfma_f32_16x16x32_bf16 v[78:81], v[178:181], v[202:205], v[78:81]
	v_mfma_f32_16x16x32_bf16 v[70:73], v[170:173], v[210:213], v[70:73]
	v_mfma_f32_16x16x32_bf16 v[66:69], v[178:181], v[210:213], v[66:69]
	v_mfma_f32_16x16x32_bf16 v[118:121], v[174:177], v[190:193], v[118:121]
	v_mfma_f32_16x16x32_bf16 v[110:113], v[182:185], v[190:193], v[110:113]
	v_mfma_f32_16x16x32_bf16 v[102:105], v[174:177], v[198:201], v[102:105]
	v_mfma_f32_16x16x32_bf16 v[94:97], v[182:185], v[198:201], v[94:97]
	v_mfma_f32_16x16x32_bf16 v[86:89], v[174:177], v[206:209], v[86:89]
	v_mfma_f32_16x16x32_bf16 v[78:81], v[182:185], v[206:209], v[78:81]
	v_mfma_f32_16x16x32_bf16 v[70:73], v[174:177], v[214:217], v[70:73]
	v_mfma_f32_16x16x32_bf16 v[66:69], v[182:185], v[214:217], v[66:69]
	s_setprio 0
	s_barrier
	s_add_i32 s4, s30, s48
	s_add_i32 m0, s4, 0xffffff80
	ds_read_b128 v[186:189], v152 offset:49152
	ds_read_b128 v[190:193], v146 offset:49152
	ds_read_b128 v[194:197], v152 offset:51200
	ds_read_b128 v[198:201], v146 offset:51200
	ds_read_b128 v[202:205], v152 offset:53248
	ds_read_b128 v[206:209], v146 offset:53248
	ds_read_b128 v[210:213], v152 offset:55296
	ds_read_b128 v[214:217], v146 offset:55296
	global_load_lds_dwordx4 v132, s[36:37] offset:128
	s_add_i32 m0, s4, 0x1f80
	s_add_u32 s4, s36, 0x160080
	s_addc_u32 s5, s37, 0
	s_add_i32 s30, s31, s48
	global_load_lds_dwordx4 v136, s[36:37] offset:128
	s_mov_b32 m0, s30
	s_nop 0
	global_load_lds_dwordx4 v132, s[4:5]
	s_add_i32 m0, s30, 0x2000
	s_nop 0
	global_load_lds_dwordx4 v136, s[4:5]
	s_waitcnt vmcnt(6)
	s_waitcnt lgkmcnt(0)
	s_barrier
	s_setprio 1
	s_waitcnt lgkmcnt(0)
	v_mfma_f32_16x16x32_bf16 v[62:65], v[154:157], v[186:189], v[62:65]
	v_mfma_f32_16x16x32_bf16 v[58:61], v[162:165], v[186:189], v[58:61]
	v_mfma_f32_16x16x32_bf16 v[50:53], v[154:157], v[194:197], v[50:53]
	v_mfma_f32_16x16x32_bf16 v[42:45], v[162:165], v[194:197], v[42:45]
	v_mfma_f32_16x16x32_bf16 v[34:37], v[154:157], v[202:205], v[34:37]
	v_mfma_f32_16x16x32_bf16 v[26:29], v[162:165], v[202:205], v[26:29]
	v_mfma_f32_16x16x32_bf16 v[18:21], v[154:157], v[210:213], v[18:21]
	v_mfma_f32_16x16x32_bf16 v[10:13], v[162:165], v[210:213], v[10:13]
	v_mfma_f32_16x16x32_bf16 v[62:65], v[158:161], v[190:193], v[62:65]
	v_mfma_f32_16x16x32_bf16 v[58:61], v[166:169], v[190:193], v[58:61]
	v_mfma_f32_16x16x32_bf16 v[50:53], v[158:161], v[198:201], v[50:53]
	v_mfma_f32_16x16x32_bf16 v[42:45], v[166:169], v[198:201], v[42:45]
	v_mfma_f32_16x16x32_bf16 v[34:37], v[158:161], v[206:209], v[34:37]
	v_mfma_f32_16x16x32_bf16 v[26:29], v[166:169], v[206:209], v[26:29]
	v_mfma_f32_16x16x32_bf16 v[18:21], v[158:161], v[214:217], v[18:21]
	v_mfma_f32_16x16x32_bf16 v[10:13], v[166:169], v[214:217], v[10:13]
	s_setprio 0
	s_setprio 1
	v_mfma_f32_16x16x32_bf16 v[54:57], v[170:173], v[186:189], v[54:57]
	v_mfma_f32_16x16x32_bf16 v[46:49], v[178:181], v[186:189], v[46:49]
	v_mfma_f32_16x16x32_bf16 v[38:41], v[170:173], v[194:197], v[38:41]
	v_mfma_f32_16x16x32_bf16 v[30:33], v[178:181], v[194:197], v[30:33]
	v_mfma_f32_16x16x32_bf16 v[22:25], v[170:173], v[202:205], v[22:25]
	v_mfma_f32_16x16x32_bf16 v[14:17], v[178:181], v[202:205], v[14:17]
	v_mfma_f32_16x16x32_bf16 v[6:9], v[170:173], v[210:213], v[6:9]
	v_mfma_f32_16x16x32_bf16 v[2:5], v[178:181], v[210:213], v[2:5]
	v_mfma_f32_16x16x32_bf16 v[54:57], v[174:177], v[190:193], v[54:57]
	v_mfma_f32_16x16x32_bf16 v[46:49], v[182:185], v[190:193], v[46:49]
	v_mfma_f32_16x16x32_bf16 v[38:41], v[174:177], v[198:201], v[38:41]
	v_mfma_f32_16x16x32_bf16 v[30:33], v[182:185], v[198:201], v[30:33]
	v_mfma_f32_16x16x32_bf16 v[22:25], v[174:177], v[206:209], v[22:25]
	v_mfma_f32_16x16x32_bf16 v[14:17], v[182:185], v[206:209], v[14:17]
	v_mfma_f32_16x16x32_bf16 v[6:9], v[174:177], v[214:217], v[6:9]
	v_mfma_f32_16x16x32_bf16 v[2:5], v[182:185], v[214:217], v[2:5]
	s_setprio 0
	s_add_i32 s74, s74, 2
	s_add_u32 s72, s72, 0x100
	s_addc_u32 s73, s73, 0
	s_cmpk_gt_u32 s74, 0x55
	s_mov_b64 s[30:31], s[34:35]
	s_barrier
	s_cbranch_scc0 .LBB0_1017
	s_and_b64 vcc, exec, s[18:19]
	s_cbranch_vccz .LBB0_1020
	s_barrier
